# P3 scan: latency-aware order also for the two tokens that had no nops, and each token's two LDS waits merged into one
# speedup vs baseline: 1.0153x; 1.0153x over previous
; #define LAS __attribute__((address_space(3)))
; __device__ __forceinline__ void rwkv_scan_prompt(const Params& p, LAS unsigned char* lds, int bh, int rq) {
;     ...
;             const LAS float* ob = OPS + buf * TC * 6 * 64;
;             f32x4 r4 = *(const LAS f32x4*)(ob + cg_ * 4), d4 = *(const LAS f32x4*)(ob + 64 + cg_ * 4), k4 = *(const LAS f32x4*)(ob + 128 + cg_ * 4),
;                   a4 = *(const LAS f32x4*)(ob + 256 + cg_ * 4), b4 = *(const LAS f32x4*)(ob + 320 + cg_ * 4);
;             float vv = ob[192 + rq * 16 + rloc];
;             f32x4 rp = r4;
; #pragma unroll
;             for (int tk = 0; tk < TC; ++tk) {
;                 f32x4 nr4 = r4, nd4 = d4, nk4 = k4, na4 = a4, nb4 = b4; float nvv = vv;
;                 if (tk < TC - 1) {
;                     const LAS float* o = ob + (tk + 1) * 6 * 64;
;                     nr4 = *(const LAS f32x4*)(o + cg_ * 4); nd4 = *(const LAS f32x4*)(o + 64 + cg_ * 4); nk4 = *(const LAS f32x4*)(o + 128 + cg_ * 4);
;                     na4 = *(const LAS f32x4*)(o + 256 + cg_ * 4); nb4 = *(const LAS f32x4*)(o + 320 + cg_ * 4);
;                     nvv = o[192 + rq * 16 + rloc];
;                 }
;                 __builtin_amdgcn_sched_barrier(0);
;                 typedef float f32x2_ __attribute__((ext_vector_type(2)));
;                 f32x2_ ta = (f32x2_){S[0], S[1]} * (f32x2_){a4[0], a4[1]}; ta = (f32x2_){S[2], S[3]} * (f32x2_){a4[2], a4[3]} + ta;
;                 f32x2_ ty = (f32x2_){S[0], S[1]} * (f32x2_){rp[0], rp[1]}; ty = (f32x2_){S[2], S[3]} * (f32x2_){rp[2], rp[3]} + ty;
;                 const f32x4 T = S * d4 + vv * k4;
;                 float sa = ta[0] + ta[1];
;                 float yp = ty[0] + ty[1];
;                 sa = dpp_add<0xB1>(sa); yp = dpp_add<0xB1>(yp);
;                 sa = dpp_add<0x4E>(sa); yp = dpp_add<0x4E>(yp);
;                 sa = dpp_add<0x124>(sa); yp = dpp_add<0x124>(yp);
;                 sa = dpp_add<0x128>(sa); yp = dpp_add<0x128>(yp);
;                 if (tk > 0) yk[(tk - 1) >> 4] = (cg_ == ((tk - 1) & 15)) ? yp : yk[(tk - 1) >> 4];
;                 S = sa * b4 + T;
;                 rp = r4;
;                 r4 = nr4; d4 = nd4; k4 = nk4; a4 = na4; b4 = nb4; vv = nvv;
.LBB0_336:
	s_and_b32 s95, s73, 1
	s_and_saveexec_b64 s[74:75], s[38:39]
	s_xor_b64 s[74:75], exec, s[74:75]
	s_cbranch_execz .LBB0_338
	s_mul_i32 s78, s95, 0xc000
	s_add_i32 s78, s78, 0
	v_lshl_add_u32 v28, v36, 2, s78
	v_lshl_add_u32 v29, v154, 2, s78
	ds_read_b128 v[30:33], v28
	ds_read_b128 v[160:163], v28 offset:256
	ds_read_b128 v[164:167], v28 offset:512
	ds_read_b128 v[168:171], v28 offset:1024
	ds_read2st64_b32 v[34:35], v29 offset0:3 offset1:9
	ds_read_b128 v[172:175], v28 offset:1280
	ds_read_b128 v[176:179], v28 offset:1536
	ds_read_b128 v[180:183], v28 offset:1792
	ds_read_b128 v[184:187], v28 offset:2048
	ds_read_b128 v[188:191], v28 offset:2560
	ds_read_b128 v[192:195], v28 offset:2816
	s_waitcnt lgkmcnt(7)
	v_pk_mul_f32 v[170:171], v[26:27], v[170:171]
	s_waitcnt lgkmcnt(6)
	v_pk_mul_f32 v[164:165], v[164:165], v[34:35] op_sel_hi:[1,0]
	v_pk_fma_f32 v[168:169], v[24:25], v[168:169], v[170:171]
	v_pk_mul_f32 v[166:167], v[166:167], v[34:35] op_sel_hi:[1,0]
	v_add_f32_e32 v168, v168, v169
	v_pk_fma_f32 v[26:27], v[26:27], v[162:163], v[166:167]
	v_pk_fma_f32 v[24:25], v[24:25], v[160:161], v[164:165]
	v_add_f32_dpp v168, v168, v168 quad_perm:[1,0,3,2] row_mask:0xf bank_mask:0xf bound_ctrl:1
	s_nop 1
	v_add_f32_dpp v168, v168, v168 quad_perm:[2,3,0,1] row_mask:0xf bank_mask:0xf bound_ctrl:1
	s_nop 1
	v_add_f32_dpp v168, v168, v168 row_ror:4 row_mask:0xf bank_mask:0xf bound_ctrl:1
	s_nop 1
	v_add_f32_dpp v168, v168, v168 row_ror:8 row_mask:0xf bank_mask:0xf bound_ctrl:1
	s_waitcnt lgkmcnt(5)
	v_pk_fma_f32 v[196:197], v[172:173], v[168:169], v[24:25] op_sel_hi:[1,0,1]
	v_pk_fma_f32 v[198:199], v[174:175], v[168:169], v[26:27] op_sel_hi:[1,0,1]
	ds_read_b128 v[24:27], v28 offset:3072
	ds_read_b128 v[160:163], v28 offset:3328
	ds_read_b128 v[164:167], v28 offset:3584
	ds_read_b128 v[168:171], v28 offset:4096
	ds_read_b128 v[172:175], v28 offset:4352
	ds_read_b32 v34, v29 offset:3840
	s_waitcnt lgkmcnt(6)
	v_pk_mul_f32 v[190:191], v[190:191], v[198:199]
	v_pk_mul_f32 v[32:33], v[32:33], v[198:199]
	v_pk_fma_f32 v[188:189], v[188:189], v[196:197], v[190:191]
	v_pk_fma_f32 v[30:31], v[30:31], v[196:197], v[32:33]
	v_pk_mul_f32 v[32:33], v[180:181], v[196:197]
	v_add_f32_e32 v206, v188, v189
	v_add_f32_e32 v30, v30, v31
	v_pk_mul_f32 v[180:181], v[182:183], v[198:199]
	v_add_f32_dpp v31, v206, v206 quad_perm:[1,0,3,2] row_mask:0xf bank_mask:0xf bound_ctrl:1
	v_add_f32_dpp v30, v30, v30 quad_perm:[1,0,3,2] row_mask:0xf bank_mask:0xf bound_ctrl:1
	v_mov_b32_e32 v182, v35
	v_add_f32_dpp v31, v31, v31 quad_perm:[2,3,0,1] row_mask:0xf bank_mask:0xf bound_ctrl:1
	v_add_f32_dpp v30, v30, v30 quad_perm:[2,3,0,1] row_mask:0xf bank_mask:0xf bound_ctrl:1
	v_pk_fma_f32 v[180:181], v[186:187], v[182:183], v[180:181] op_sel_hi:[1,0,1]
	v_add_f32_dpp v31, v31, v31 row_ror:4 row_mask:0xf bank_mask:0xf bound_ctrl:1
	v_add_f32_dpp v35, v30, v30 row_ror:4 row_mask:0xf bank_mask:0xf bound_ctrl:1
	v_pk_fma_f32 v[32:33], v[184:185], v[182:183], v[32:33] op_sel_hi:[1,0,1]
	v_add_f32_dpp v30, v31, v31 row_ror:8 row_mask:0xf bank_mask:0xf bound_ctrl:1
	v_add_f32_dpp v31, v35, v35 row_ror:8 row_mask:0xf bank_mask:0xf bound_ctrl:1
	v_pk_fma_f32 v[196:197], v[192:193], v[30:31], v[32:33] op_sel_hi:[1,0,1]
	v_cndmask_b32_e64 v201, 0, v31, s[6:7]
	v_pk_fma_f32 v[198:199], v[194:195], v[30:31], v[180:181] op_sel_hi:[1,0,1]
	ds_read_b128 v[30:33], v28 offset:4608
	ds_read_b128 v[180:183], v28 offset:4864
	ds_read_b128 v[184:187], v28 offset:5120
	ds_read_b128 v[188:191], v28 offset:5632
	ds_read_b128 v[192:195], v28 offset:5888
	ds_read_b32 v200, v29 offset:5376
	s_waitcnt lgkmcnt(6)
	v_pk_mul_f32 v[170:171], v[170:171], v[198:199]
	v_pk_mul_f32 v[160:161], v[160:161], v[196:197]
	v_pk_fma_f32 v[168:169], v[168:169], v[196:197], v[170:171]
	v_pk_mul_f32 v[170:171], v[178:179], v[198:199]
	v_pk_mul_f32 v[162:163], v[162:163], v[198:199]
	v_pk_fma_f32 v[170:171], v[176:177], v[196:197], v[170:171]
	v_pk_fma_f32 v[162:163], v[166:167], v[34:35], v[162:163] op_sel_hi:[1,0,1]
	v_add_f32_e32 v206, v168, v169
	v_pk_fma_f32 v[34:35], v[164:165], v[34:35], v[160:161] op_sel_hi:[1,0,1]
	v_add_f32_e32 v161, v170, v171
	v_add_f32_dpp v160, v206, v206 quad_perm:[1,0,3,2] row_mask:0xf bank_mask:0xf bound_ctrl:1
	s_nop 0
	v_add_f32_dpp v161, v161, v161 quad_perm:[1,0,3,2] row_mask:0xf bank_mask:0xf bound_ctrl:1
	v_add_f32_dpp v160, v160, v160 quad_perm:[2,3,0,1] row_mask:0xf bank_mask:0xf bound_ctrl:1
	s_nop 0
	v_add_f32_dpp v161, v161, v161 quad_perm:[2,3,0,1] row_mask:0xf bank_mask:0xf bound_ctrl:1
	v_add_f32_dpp v160, v160, v160 row_ror:4 row_mask:0xf bank_mask:0xf bound_ctrl:1
	s_nop 0
	v_add_f32_dpp v161, v161, v161 row_ror:4 row_mask:0xf bank_mask:0xf bound_ctrl:1
	v_add_f32_dpp v160, v160, v160 row_ror:8 row_mask:0xf bank_mask:0xf bound_ctrl:1
	v_pk_fma_f32 v[34:35], v[172:173], v[160:161], v[34:35] op_sel_hi:[1,0,1]
	v_add_f32_dpp v161, v161, v161 row_ror:8 row_mask:0xf bank_mask:0xf bound_ctrl:1
	v_cndmask_b32_e64 v199, v201, v161, s[8:9]
	v_pk_fma_f32 v[196:197], v[174:175], v[160:161], v[162:163] op_sel_hi:[1,0,1]
	ds_read_b128 v[160:163], v28 offset:6144
	ds_read_b128 v[164:167], v28 offset:6400
	ds_read_b128 v[168:171], v28 offset:6656
	ds_read_b128 v[172:175], v28 offset:7168
	ds_read_b128 v[176:179], v28 offset:7424
	ds_read_b32 v198, v29 offset:6912
	s_waitcnt lgkmcnt(6)
; #define LAS __attribute__((address_space(3)))
; __device__ __forceinline__ void rwkv_scan_prompt(const Params& p, LAS unsigned char* lds, int bh, int rq) {
;     ...
;             for (int tk = 0; tk < TC; ++tk) {
;                 f32x4 nr4 = r4, nd4 = d4, nk4 = k4, na4 = a4, nb4 = b4; float nvv = vv;
;                 if (tk < TC - 1) {
;                     const LAS float* o = ob + (tk + 1) * 6 * 64;
;                     nr4 = *(const LAS f32x4*)(o + cg_ * 4); nd4 = *(const LAS f32x4*)(o + 64 + cg_ * 4); nk4 = *(const LAS f32x4*)(o + 128 + cg_ * 4);
;                     na4 = *(const LAS f32x4*)(o + 256 + cg_ * 4); nb4 = *(const LAS f32x4*)(o + 320 + cg_ * 4);
;                     nvv = o[192 + rq * 16 + rloc];
;                 }
;                 __builtin_amdgcn_sched_barrier(0);
;                 typedef float f32x2_ __attribute__((ext_vector_type(2)));
;                 f32x2_ ta = (f32x2_){S[0], S[1]} * (f32x2_){a4[0], a4[1]}; ta = (f32x2_){S[2], S[3]} * (f32x2_){a4[2], a4[3]} + ta;
;                 f32x2_ ty = (f32x2_){S[0], S[1]} * (f32x2_){rp[0], rp[1]}; ty = (f32x2_){S[2], S[3]} * (f32x2_){rp[2], rp[3]} + ty;
;                 const f32x4 T = S * d4 + vv * k4;
;                 float sa = ta[0] + ta[1];
;                 float yp = ty[0] + ty[1];
;                 sa = dpp_add<0xB1>(sa); yp = dpp_add<0xB1>(yp);
;                 sa = dpp_add<0x4E>(sa); yp = dpp_add<0x4E>(yp);
;                 sa = dpp_add<0x124>(sa); yp = dpp_add<0x124>(yp);
;                 sa = dpp_add<0x128>(sa); yp = dpp_add<0x128>(yp);
;                 if (tk > 0) yk[(tk - 1) >> 4] = (cg_ == ((tk - 1) & 15)) ? yp : yk[(tk - 1) >> 4];
;                 S = sa * b4 + T;
;                 rp = r4;
;                 r4 = nr4; d4 = nd4; k4 = nk4; a4 = na4; b4 = nb4; vv = nvv;
	v_pk_mul_f32 v[190:191], v[190:191], v[196:197]
	v_pk_mul_f32 v[26:27], v[26:27], v[196:197]
	v_pk_fma_f32 v[188:189], v[188:189], v[34:35], v[190:191]
	v_pk_fma_f32 v[24:25], v[24:25], v[34:35], v[26:27]
	v_add_f32_e32 v206, v188, v189
	v_add_f32_e32 v24, v24, v25
	v_pk_mul_f32 v[26:27], v[180:181], v[34:35]
	v_add_f32_dpp v25, v206, v206 quad_perm:[1,0,3,2] row_mask:0xf bank_mask:0xf bound_ctrl:1
	v_add_f32_dpp v24, v24, v24 quad_perm:[1,0,3,2] row_mask:0xf bank_mask:0xf bound_ctrl:1
	v_pk_mul_f32 v[34:35], v[182:183], v[196:197]
	v_add_f32_dpp v25, v25, v25 quad_perm:[2,3,0,1] row_mask:0xf bank_mask:0xf bound_ctrl:1
	v_add_f32_dpp v24, v24, v24 quad_perm:[2,3,0,1] row_mask:0xf bank_mask:0xf bound_ctrl:1
	v_pk_fma_f32 v[34:35], v[186:187], v[200:201], v[34:35] op_sel_hi:[1,0,1]
	v_add_f32_dpp v25, v25, v25 row_ror:4 row_mask:0xf bank_mask:0xf bound_ctrl:1
	v_add_f32_dpp v180, v24, v24 row_ror:4 row_mask:0xf bank_mask:0xf bound_ctrl:1
	v_pk_fma_f32 v[26:27], v[184:185], v[200:201], v[26:27] op_sel_hi:[1,0,1]
	v_add_f32_dpp v24, v25, v25 row_ror:8 row_mask:0xf bank_mask:0xf bound_ctrl:1
	v_add_f32_dpp v25, v180, v180 row_ror:8 row_mask:0xf bank_mask:0xf bound_ctrl:1
	v_pk_fma_f32 v[196:197], v[192:193], v[24:25], v[26:27] op_sel_hi:[1,0,1]
	v_cndmask_b32_e64 v199, v199, v25, s[10:11]
	v_pk_fma_f32 v[34:35], v[194:195], v[24:25], v[34:35] op_sel_hi:[1,0,1]
	ds_read_b128 v[24:27], v28 offset:7680
	ds_read_b128 v[180:183], v28 offset:7936
	ds_read_b128 v[184:187], v28 offset:8192
	ds_read_b128 v[188:191], v28 offset:8704
	ds_read_b128 v[192:195], v28 offset:8960
	ds_read_b32 v200, v29 offset:8448
	s_waitcnt lgkmcnt(6)
	v_pk_mul_f32 v[174:175], v[174:175], v[34:35]
	v_pk_mul_f32 v[32:33], v[32:33], v[34:35]
	v_pk_fma_f32 v[172:173], v[172:173], v[196:197], v[174:175]
	v_pk_fma_f32 v[30:31], v[30:31], v[196:197], v[32:33]
	v_add_f32_e32 v206, v172, v173
	v_add_f32_e32 v30, v30, v31
	v_pk_mul_f32 v[32:33], v[164:165], v[196:197]
	v_add_f32_dpp v31, v206, v206 quad_perm:[1,0,3,2] row_mask:0xf bank_mask:0xf bound_ctrl:1
	v_add_f32_dpp v30, v30, v30 quad_perm:[1,0,3,2] row_mask:0xf bank_mask:0xf bound_ctrl:1
	v_pk_mul_f32 v[34:35], v[166:167], v[34:35]
	v_add_f32_dpp v31, v31, v31 quad_perm:[2,3,0,1] row_mask:0xf bank_mask:0xf bound_ctrl:1
	v_add_f32_dpp v30, v30, v30 quad_perm:[2,3,0,1] row_mask:0xf bank_mask:0xf bound_ctrl:1
	v_pk_fma_f32 v[34:35], v[170:171], v[198:199], v[34:35] op_sel_hi:[1,0,1]
	v_add_f32_dpp v31, v31, v31 row_ror:4 row_mask:0xf bank_mask:0xf bound_ctrl:1
	v_add_f32_dpp v164, v30, v30 row_ror:4 row_mask:0xf bank_mask:0xf bound_ctrl:1
	v_pk_fma_f32 v[32:33], v[168:169], v[198:199], v[32:33] op_sel_hi:[1,0,1]
	v_add_f32_dpp v30, v31, v31 row_ror:8 row_mask:0xf bank_mask:0xf bound_ctrl:1
	v_add_f32_dpp v31, v164, v164 row_ror:8 row_mask:0xf bank_mask:0xf bound_ctrl:1
	v_pk_fma_f32 v[196:197], v[176:177], v[30:31], v[32:33] op_sel_hi:[1,0,1]
	v_cndmask_b32_e64 v199, v199, v31, s[12:13]
	v_pk_fma_f32 v[34:35], v[178:179], v[30:31], v[34:35] op_sel_hi:[1,0,1]
	ds_read_b128 v[30:33], v28 offset:9216
	ds_read_b128 v[164:167], v28 offset:9472
	ds_read_b128 v[168:171], v28 offset:9728
	ds_read_b128 v[172:175], v28 offset:10240
	ds_read_b128 v[176:179], v28 offset:10496
	ds_read_b32 v198, v29 offset:9984
	s_waitcnt lgkmcnt(6)
	v_pk_mul_f32 v[190:191], v[190:191], v[34:35]
	v_pk_mul_f32 v[162:163], v[162:163], v[34:35]
	v_pk_fma_f32 v[188:189], v[188:189], v[196:197], v[190:191]
	v_pk_fma_f32 v[160:161], v[160:161], v[196:197], v[162:163]
	v_add_f32_e32 v206, v188, v189
	v_add_f32_e32 v160, v160, v161
	v_pk_mul_f32 v[162:163], v[180:181], v[196:197]
	v_add_f32_dpp v161, v206, v206 quad_perm:[1,0,3,2] row_mask:0xf bank_mask:0xf bound_ctrl:1
	v_add_f32_dpp v160, v160, v160 quad_perm:[1,0,3,2] row_mask:0xf bank_mask:0xf bound_ctrl:1
	v_pk_mul_f32 v[34:35], v[182:183], v[34:35]
	v_add_f32_dpp v161, v161, v161 quad_perm:[2,3,0,1] row_mask:0xf bank_mask:0xf bound_ctrl:1
	v_add_f32_dpp v160, v160, v160 quad_perm:[2,3,0,1] row_mask:0xf bank_mask:0xf bound_ctrl:1
	v_pk_fma_f32 v[34:35], v[186:187], v[200:201], v[34:35] op_sel_hi:[1,0,1]
	v_add_f32_dpp v161, v161, v161 row_ror:4 row_mask:0xf bank_mask:0xf bound_ctrl:1
	v_add_f32_dpp v180, v160, v160 row_ror:4 row_mask:0xf bank_mask:0xf bound_ctrl:1
	v_pk_fma_f32 v[162:163], v[184:185], v[200:201], v[162:163] op_sel_hi:[1,0,1]
	v_add_f32_dpp v160, v161, v161 row_ror:8 row_mask:0xf bank_mask:0xf bound_ctrl:1
	v_add_f32_dpp v161, v180, v180 row_ror:8 row_mask:0xf bank_mask:0xf bound_ctrl:1
	v_pk_fma_f32 v[196:197], v[192:193], v[160:161], v[162:163] op_sel_hi:[1,0,1]
	v_cndmask_b32_e64 v199, v199, v161, s[14:15]
	v_pk_fma_f32 v[34:35], v[194:195], v[160:161], v[34:35] op_sel_hi:[1,0,1]
	ds_read_b128 v[160:163], v28 offset:10752
	ds_read_b128 v[180:183], v28 offset:11008
	ds_read_b128 v[184:187], v28 offset:11264
	ds_read_b128 v[188:191], v28 offset:11776
	ds_read_b128 v[192:195], v28 offset:12032
	ds_read_b32 v200, v29 offset:11520
	s_waitcnt lgkmcnt(6)
; #define LAS __attribute__((address_space(3)))
; __device__ __forceinline__ void rwkv_scan_prompt(const Params& p, LAS unsigned char* lds, int bh, int rq) {
;     ...
;             for (int tk = 0; tk < TC; ++tk) {
;                 f32x4 nr4 = r4, nd4 = d4, nk4 = k4, na4 = a4, nb4 = b4; float nvv = vv;
;                 if (tk < TC - 1) {
;                     const LAS float* o = ob + (tk + 1) * 6 * 64;
;                     nr4 = *(const LAS f32x4*)(o + cg_ * 4); nd4 = *(const LAS f32x4*)(o + 64 + cg_ * 4); nk4 = *(const LAS f32x4*)(o + 128 + cg_ * 4);
;                     na4 = *(const LAS f32x4*)(o + 256 + cg_ * 4); nb4 = *(const LAS f32x4*)(o + 320 + cg_ * 4);
;                     nvv = o[192 + rq * 16 + rloc];
;                 }
;                 __builtin_amdgcn_sched_barrier(0);
;                 typedef float f32x2_ __attribute__((ext_vector_type(2)));
;                 f32x2_ ta = (f32x2_){S[0], S[1]} * (f32x2_){a4[0], a4[1]}; ta = (f32x2_){S[2], S[3]} * (f32x2_){a4[2], a4[3]} + ta;
;                 f32x2_ ty = (f32x2_){S[0], S[1]} * (f32x2_){rp[0], rp[1]}; ty = (f32x2_){S[2], S[3]} * (f32x2_){rp[2], rp[3]} + ty;
;                 const f32x4 T = S * d4 + vv * k4;
;                 float sa = ta[0] + ta[1];
;                 float yp = ty[0] + ty[1];
;                 sa = dpp_add<0xB1>(sa); yp = dpp_add<0xB1>(yp);
;                 sa = dpp_add<0x4E>(sa); yp = dpp_add<0x4E>(yp);
;                 sa = dpp_add<0x124>(sa); yp = dpp_add<0x124>(yp);
;                 sa = dpp_add<0x128>(sa); yp = dpp_add<0x128>(yp);
;                 if (tk > 0) yk[(tk - 1) >> 4] = (cg_ == ((tk - 1) & 15)) ? yp : yk[(tk - 1) >> 4];
;                 S = sa * b4 + T;
;                 rp = r4;
;                 r4 = nr4; d4 = nd4; k4 = nk4; a4 = na4; b4 = nb4; vv = nvv;
	v_pk_mul_f32 v[174:175], v[174:175], v[34:35]
	v_pk_mul_f32 v[26:27], v[26:27], v[34:35]
	v_pk_fma_f32 v[172:173], v[172:173], v[196:197], v[174:175]
	v_pk_fma_f32 v[24:25], v[24:25], v[196:197], v[26:27]
	v_add_f32_e32 v206, v172, v173
	v_add_f32_e32 v24, v24, v25
	v_pk_mul_f32 v[26:27], v[164:165], v[196:197]
	v_add_f32_dpp v25, v206, v206 quad_perm:[1,0,3,2] row_mask:0xf bank_mask:0xf bound_ctrl:1
	v_add_f32_dpp v24, v24, v24 quad_perm:[1,0,3,2] row_mask:0xf bank_mask:0xf bound_ctrl:1
	v_pk_mul_f32 v[34:35], v[166:167], v[34:35]
	v_add_f32_dpp v25, v25, v25 quad_perm:[2,3,0,1] row_mask:0xf bank_mask:0xf bound_ctrl:1
	v_add_f32_dpp v24, v24, v24 quad_perm:[2,3,0,1] row_mask:0xf bank_mask:0xf bound_ctrl:1
	v_pk_fma_f32 v[34:35], v[170:171], v[198:199], v[34:35] op_sel_hi:[1,0,1]
	v_add_f32_dpp v25, v25, v25 row_ror:4 row_mask:0xf bank_mask:0xf bound_ctrl:1
	v_add_f32_dpp v164, v24, v24 row_ror:4 row_mask:0xf bank_mask:0xf bound_ctrl:1
	v_pk_fma_f32 v[26:27], v[168:169], v[198:199], v[26:27] op_sel_hi:[1,0,1]
	v_add_f32_dpp v24, v25, v25 row_ror:8 row_mask:0xf bank_mask:0xf bound_ctrl:1
	v_add_f32_dpp v25, v164, v164 row_ror:8 row_mask:0xf bank_mask:0xf bound_ctrl:1
	v_pk_fma_f32 v[196:197], v[176:177], v[24:25], v[26:27] op_sel_hi:[1,0,1]
	v_cndmask_b32_e64 v199, v199, v25, s[16:17]
	v_pk_fma_f32 v[34:35], v[178:179], v[24:25], v[34:35] op_sel_hi:[1,0,1]
	ds_read_b128 v[24:27], v28 offset:12288
	ds_read_b128 v[164:167], v28 offset:12544
	ds_read_b128 v[168:171], v28 offset:12800
	ds_read_b128 v[172:175], v28 offset:13312
	ds_read_b128 v[176:179], v28 offset:13568
	ds_read_b32 v198, v29 offset:13056
	s_waitcnt lgkmcnt(6)
	v_pk_mul_f32 v[190:191], v[190:191], v[34:35]
	v_pk_mul_f32 v[32:33], v[32:33], v[34:35]
	v_pk_fma_f32 v[188:189], v[188:189], v[196:197], v[190:191]
	v_pk_fma_f32 v[30:31], v[30:31], v[196:197], v[32:33]
	v_add_f32_e32 v206, v188, v189
	v_add_f32_e32 v30, v30, v31
	v_pk_mul_f32 v[32:33], v[180:181], v[196:197]
	v_add_f32_dpp v31, v206, v206 quad_perm:[1,0,3,2] row_mask:0xf bank_mask:0xf bound_ctrl:1
	v_add_f32_dpp v30, v30, v30 quad_perm:[1,0,3,2] row_mask:0xf bank_mask:0xf bound_ctrl:1
	v_pk_mul_f32 v[34:35], v[182:183], v[34:35]
	v_add_f32_dpp v31, v31, v31 quad_perm:[2,3,0,1] row_mask:0xf bank_mask:0xf bound_ctrl:1
	v_add_f32_dpp v30, v30, v30 quad_perm:[2,3,0,1] row_mask:0xf bank_mask:0xf bound_ctrl:1
	v_pk_fma_f32 v[34:35], v[186:187], v[200:201], v[34:35] op_sel_hi:[1,0,1]
	v_add_f32_dpp v31, v31, v31 row_ror:4 row_mask:0xf bank_mask:0xf bound_ctrl:1
	v_add_f32_dpp v180, v30, v30 row_ror:4 row_mask:0xf bank_mask:0xf bound_ctrl:1
	v_pk_fma_f32 v[32:33], v[184:185], v[200:201], v[32:33] op_sel_hi:[1,0,1]
	v_add_f32_dpp v30, v31, v31 row_ror:8 row_mask:0xf bank_mask:0xf bound_ctrl:1
	v_add_f32_dpp v31, v180, v180 row_ror:8 row_mask:0xf bank_mask:0xf bound_ctrl:1
	v_pk_fma_f32 v[196:197], v[192:193], v[30:31], v[32:33] op_sel_hi:[1,0,1]
	v_cndmask_b32_e64 v199, v199, v31, s[18:19]
	v_pk_fma_f32 v[34:35], v[194:195], v[30:31], v[34:35] op_sel_hi:[1,0,1]
	ds_read_b128 v[30:33], v28 offset:13824
	ds_read_b128 v[180:183], v28 offset:14080
	ds_read_b128 v[184:187], v28 offset:14336
	ds_read_b128 v[188:191], v28 offset:14848
	ds_read_b128 v[192:195], v28 offset:15104
	ds_read_b32 v200, v29 offset:14592
	s_waitcnt lgkmcnt(6)
	v_pk_mul_f32 v[174:175], v[174:175], v[34:35]
	v_pk_mul_f32 v[162:163], v[162:163], v[34:35]
	v_pk_fma_f32 v[172:173], v[172:173], v[196:197], v[174:175]
	v_pk_fma_f32 v[160:161], v[160:161], v[196:197], v[162:163]
	v_add_f32_e32 v206, v172, v173
	v_add_f32_e32 v160, v160, v161
	v_pk_mul_f32 v[162:163], v[164:165], v[196:197]
	v_add_f32_dpp v161, v206, v206 quad_perm:[1,0,3,2] row_mask:0xf bank_mask:0xf bound_ctrl:1
	v_add_f32_dpp v160, v160, v160 quad_perm:[1,0,3,2] row_mask:0xf bank_mask:0xf bound_ctrl:1
	v_pk_mul_f32 v[34:35], v[166:167], v[34:35]
	v_add_f32_dpp v161, v161, v161 quad_perm:[2,3,0,1] row_mask:0xf bank_mask:0xf bound_ctrl:1
	v_add_f32_dpp v160, v160, v160 quad_perm:[2,3,0,1] row_mask:0xf bank_mask:0xf bound_ctrl:1
	v_pk_fma_f32 v[34:35], v[170:171], v[198:199], v[34:35] op_sel_hi:[1,0,1]
	v_add_f32_dpp v161, v161, v161 row_ror:4 row_mask:0xf bank_mask:0xf bound_ctrl:1
	v_add_f32_dpp v164, v160, v160 row_ror:4 row_mask:0xf bank_mask:0xf bound_ctrl:1
	v_pk_fma_f32 v[162:163], v[168:169], v[198:199], v[162:163] op_sel_hi:[1,0,1]
	v_add_f32_dpp v160, v161, v161 row_ror:8 row_mask:0xf bank_mask:0xf bound_ctrl:1
	v_add_f32_dpp v161, v164, v164 row_ror:8 row_mask:0xf bank_mask:0xf bound_ctrl:1
	v_pk_fma_f32 v[196:197], v[176:177], v[160:161], v[162:163] op_sel_hi:[1,0,1]
	v_cndmask_b32_e64 v199, v199, v161, s[20:21]
	v_pk_fma_f32 v[34:35], v[178:179], v[160:161], v[34:35] op_sel_hi:[1,0,1]
	ds_read_b128 v[160:163], v28 offset:15360
	ds_read_b128 v[164:167], v28 offset:15616
	ds_read_b128 v[168:171], v28 offset:15872
	ds_read_b128 v[172:175], v28 offset:16384
	ds_read_b128 v[176:179], v28 offset:16640
	ds_read_b32 v198, v29 offset:16128
	s_waitcnt lgkmcnt(6)
; #define LAS __attribute__((address_space(3)))
; __device__ __forceinline__ void rwkv_scan_prompt(const Params& p, LAS unsigned char* lds, int bh, int rq) {
;     ...
;             for (int tk = 0; tk < TC; ++tk) {
;                 f32x4 nr4 = r4, nd4 = d4, nk4 = k4, na4 = a4, nb4 = b4; float nvv = vv;
;                 if (tk < TC - 1) {
;                     const LAS float* o = ob + (tk + 1) * 6 * 64;
;                     nr4 = *(const LAS f32x4*)(o + cg_ * 4); nd4 = *(const LAS f32x4*)(o + 64 + cg_ * 4); nk4 = *(const LAS f32x4*)(o + 128 + cg_ * 4);
;                     na4 = *(const LAS f32x4*)(o + 256 + cg_ * 4); nb4 = *(const LAS f32x4*)(o + 320 + cg_ * 4);
;                     nvv = o[192 + rq * 16 + rloc];
;                 }
;                 __builtin_amdgcn_sched_barrier(0);
;                 typedef float f32x2_ __attribute__((ext_vector_type(2)));
;                 f32x2_ ta = (f32x2_){S[0], S[1]} * (f32x2_){a4[0], a4[1]}; ta = (f32x2_){S[2], S[3]} * (f32x2_){a4[2], a4[3]} + ta;
;                 f32x2_ ty = (f32x2_){S[0], S[1]} * (f32x2_){rp[0], rp[1]}; ty = (f32x2_){S[2], S[3]} * (f32x2_){rp[2], rp[3]} + ty;
;                 const f32x4 T = S * d4 + vv * k4;
;                 float sa = ta[0] + ta[1];
;                 float yp = ty[0] + ty[1];
;                 sa = dpp_add<0xB1>(sa); yp = dpp_add<0xB1>(yp);
;                 sa = dpp_add<0x4E>(sa); yp = dpp_add<0x4E>(yp);
;                 sa = dpp_add<0x124>(sa); yp = dpp_add<0x124>(yp);
;                 sa = dpp_add<0x128>(sa); yp = dpp_add<0x128>(yp);
;                 if (tk > 0) yk[(tk - 1) >> 4] = (cg_ == ((tk - 1) & 15)) ? yp : yk[(tk - 1) >> 4];
;                 S = sa * b4 + T;
;                 rp = r4;
;                 r4 = nr4; d4 = nd4; k4 = nk4; a4 = na4; b4 = nb4; vv = nvv;
	v_pk_mul_f32 v[190:191], v[190:191], v[34:35]
	v_pk_mul_f32 v[26:27], v[26:27], v[34:35]
	v_pk_fma_f32 v[188:189], v[188:189], v[196:197], v[190:191]
	v_pk_fma_f32 v[24:25], v[24:25], v[196:197], v[26:27]
	v_add_f32_e32 v206, v188, v189
	v_add_f32_e32 v24, v24, v25
	v_pk_mul_f32 v[26:27], v[180:181], v[196:197]
	v_add_f32_dpp v25, v206, v206 quad_perm:[1,0,3,2] row_mask:0xf bank_mask:0xf bound_ctrl:1
	v_add_f32_dpp v24, v24, v24 quad_perm:[1,0,3,2] row_mask:0xf bank_mask:0xf bound_ctrl:1
	v_pk_mul_f32 v[34:35], v[182:183], v[34:35]
	v_add_f32_dpp v25, v25, v25 quad_perm:[2,3,0,1] row_mask:0xf bank_mask:0xf bound_ctrl:1
	v_add_f32_dpp v24, v24, v24 quad_perm:[2,3,0,1] row_mask:0xf bank_mask:0xf bound_ctrl:1
	v_pk_fma_f32 v[34:35], v[186:187], v[200:201], v[34:35] op_sel_hi:[1,0,1]
	v_add_f32_dpp v25, v25, v25 row_ror:4 row_mask:0xf bank_mask:0xf bound_ctrl:1
	v_add_f32_dpp v180, v24, v24 row_ror:4 row_mask:0xf bank_mask:0xf bound_ctrl:1
	v_pk_fma_f32 v[26:27], v[184:185], v[200:201], v[26:27] op_sel_hi:[1,0,1]
	v_add_f32_dpp v24, v25, v25 row_ror:8 row_mask:0xf bank_mask:0xf bound_ctrl:1
	v_add_f32_dpp v25, v180, v180 row_ror:8 row_mask:0xf bank_mask:0xf bound_ctrl:1
	v_pk_fma_f32 v[196:197], v[192:193], v[24:25], v[26:27] op_sel_hi:[1,0,1]
	v_cndmask_b32_e64 v199, v199, v25, s[22:23]
	v_pk_fma_f32 v[34:35], v[194:195], v[24:25], v[34:35] op_sel_hi:[1,0,1]
	ds_read_b128 v[24:27], v28 offset:16896
	ds_read_b128 v[180:183], v28 offset:17152
	ds_read_b128 v[184:187], v28 offset:17408
	ds_read_b128 v[188:191], v28 offset:17920
	ds_read_b128 v[192:195], v28 offset:18176
	ds_read_b32 v200, v29 offset:17664
	s_waitcnt lgkmcnt(6)
	v_pk_mul_f32 v[174:175], v[174:175], v[34:35]
	v_pk_mul_f32 v[32:33], v[32:33], v[34:35]
	v_pk_fma_f32 v[172:173], v[172:173], v[196:197], v[174:175]
	v_pk_fma_f32 v[30:31], v[30:31], v[196:197], v[32:33]
	v_add_f32_e32 v206, v172, v173
	v_add_f32_e32 v30, v30, v31
	v_pk_mul_f32 v[32:33], v[164:165], v[196:197]
	v_add_f32_dpp v31, v206, v206 quad_perm:[1,0,3,2] row_mask:0xf bank_mask:0xf bound_ctrl:1
	v_add_f32_dpp v30, v30, v30 quad_perm:[1,0,3,2] row_mask:0xf bank_mask:0xf bound_ctrl:1
	v_pk_mul_f32 v[34:35], v[166:167], v[34:35]
	v_add_f32_dpp v31, v31, v31 quad_perm:[2,3,0,1] row_mask:0xf bank_mask:0xf bound_ctrl:1
	v_add_f32_dpp v30, v30, v30 quad_perm:[2,3,0,1] row_mask:0xf bank_mask:0xf bound_ctrl:1
	v_pk_fma_f32 v[34:35], v[170:171], v[198:199], v[34:35] op_sel_hi:[1,0,1]
	v_add_f32_dpp v31, v31, v31 row_ror:4 row_mask:0xf bank_mask:0xf bound_ctrl:1
	v_add_f32_dpp v164, v30, v30 row_ror:4 row_mask:0xf bank_mask:0xf bound_ctrl:1
	v_pk_fma_f32 v[32:33], v[168:169], v[198:199], v[32:33] op_sel_hi:[1,0,1]
	v_add_f32_dpp v30, v31, v31 row_ror:8 row_mask:0xf bank_mask:0xf bound_ctrl:1
	v_add_f32_dpp v31, v164, v164 row_ror:8 row_mask:0xf bank_mask:0xf bound_ctrl:1
	v_pk_fma_f32 v[196:197], v[176:177], v[30:31], v[32:33] op_sel_hi:[1,0,1]
	v_cndmask_b32_e64 v199, v199, v31, s[24:25]
	v_pk_fma_f32 v[34:35], v[178:179], v[30:31], v[34:35] op_sel_hi:[1,0,1]
	ds_read_b128 v[30:33], v28 offset:18432
	ds_read_b128 v[164:167], v28 offset:18688
	ds_read_b128 v[168:171], v28 offset:18944
	ds_read_b128 v[172:175], v28 offset:19456
	ds_read_b128 v[176:179], v28 offset:19712
	ds_read_b32 v198, v29 offset:19200
	s_waitcnt lgkmcnt(6)
	v_pk_mul_f32 v[190:191], v[190:191], v[34:35]
	v_pk_mul_f32 v[162:163], v[162:163], v[34:35]
	v_pk_fma_f32 v[188:189], v[188:189], v[196:197], v[190:191]
	v_pk_fma_f32 v[160:161], v[160:161], v[196:197], v[162:163]
	v_add_f32_e32 v206, v188, v189
	v_add_f32_e32 v160, v160, v161
	v_pk_mul_f32 v[162:163], v[180:181], v[196:197]
	v_add_f32_dpp v161, v206, v206 quad_perm:[1,0,3,2] row_mask:0xf bank_mask:0xf bound_ctrl:1
	v_add_f32_dpp v160, v160, v160 quad_perm:[1,0,3,2] row_mask:0xf bank_mask:0xf bound_ctrl:1
	v_pk_mul_f32 v[34:35], v[182:183], v[34:35]
	v_add_f32_dpp v161, v161, v161 quad_perm:[2,3,0,1] row_mask:0xf bank_mask:0xf bound_ctrl:1
	v_add_f32_dpp v160, v160, v160 quad_perm:[2,3,0,1] row_mask:0xf bank_mask:0xf bound_ctrl:1
	v_pk_fma_f32 v[34:35], v[186:187], v[200:201], v[34:35] op_sel_hi:[1,0,1]
	v_add_f32_dpp v161, v161, v161 row_ror:4 row_mask:0xf bank_mask:0xf bound_ctrl:1
	v_add_f32_dpp v180, v160, v160 row_ror:4 row_mask:0xf bank_mask:0xf bound_ctrl:1
	v_pk_fma_f32 v[162:163], v[184:185], v[200:201], v[162:163] op_sel_hi:[1,0,1]
	v_add_f32_dpp v160, v161, v161 row_ror:8 row_mask:0xf bank_mask:0xf bound_ctrl:1
	v_add_f32_dpp v161, v180, v180 row_ror:8 row_mask:0xf bank_mask:0xf bound_ctrl:1
	v_pk_fma_f32 v[196:197], v[192:193], v[160:161], v[162:163] op_sel_hi:[1,0,1]
	v_cndmask_b32_e64 v199, v199, v161, s[26:27]
	v_pk_fma_f32 v[34:35], v[194:195], v[160:161], v[34:35] op_sel_hi:[1,0,1]
	ds_read_b128 v[160:163], v28 offset:19968
	ds_read_b128 v[180:183], v28 offset:20224
	ds_read_b128 v[184:187], v28 offset:20480
	ds_read_b128 v[188:191], v28 offset:20992
	ds_read_b128 v[192:195], v28 offset:21248
	ds_read_b32 v200, v29 offset:20736
	s_waitcnt lgkmcnt(6)
; #define LAS __attribute__((address_space(3)))
; __device__ __forceinline__ void rwkv_scan_prompt(const Params& p, LAS unsigned char* lds, int bh, int rq) {
;     ...
;             for (int tk = 0; tk < TC; ++tk) {
;                 f32x4 nr4 = r4, nd4 = d4, nk4 = k4, na4 = a4, nb4 = b4; float nvv = vv;
;                 if (tk < TC - 1) {
;                     const LAS float* o = ob + (tk + 1) * 6 * 64;
;                     nr4 = *(const LAS f32x4*)(o + cg_ * 4); nd4 = *(const LAS f32x4*)(o + 64 + cg_ * 4); nk4 = *(const LAS f32x4*)(o + 128 + cg_ * 4);
;                     na4 = *(const LAS f32x4*)(o + 256 + cg_ * 4); nb4 = *(const LAS f32x4*)(o + 320 + cg_ * 4);
;                     nvv = o[192 + rq * 16 + rloc];
;                 }
;                 __builtin_amdgcn_sched_barrier(0);
;                 typedef float f32x2_ __attribute__((ext_vector_type(2)));
;                 f32x2_ ta = (f32x2_){S[0], S[1]} * (f32x2_){a4[0], a4[1]}; ta = (f32x2_){S[2], S[3]} * (f32x2_){a4[2], a4[3]} + ta;
;                 f32x2_ ty = (f32x2_){S[0], S[1]} * (f32x2_){rp[0], rp[1]}; ty = (f32x2_){S[2], S[3]} * (f32x2_){rp[2], rp[3]} + ty;
;                 const f32x4 T = S * d4 + vv * k4;
;                 float sa = ta[0] + ta[1];
;                 float yp = ty[0] + ty[1];
;                 sa = dpp_add<0xB1>(sa); yp = dpp_add<0xB1>(yp);
;                 sa = dpp_add<0x4E>(sa); yp = dpp_add<0x4E>(yp);
;                 sa = dpp_add<0x124>(sa); yp = dpp_add<0x124>(yp);
;                 sa = dpp_add<0x128>(sa); yp = dpp_add<0x128>(yp);
;                 if (tk > 0) yk[(tk - 1) >> 4] = (cg_ == ((tk - 1) & 15)) ? yp : yk[(tk - 1) >> 4];
;                 S = sa * b4 + T;
;                 rp = r4;
;                 r4 = nr4; d4 = nd4; k4 = nk4; a4 = na4; b4 = nb4; vv = nvv;
	v_pk_mul_f32 v[174:175], v[174:175], v[34:35]
	v_pk_mul_f32 v[26:27], v[26:27], v[34:35]
	v_pk_fma_f32 v[172:173], v[172:173], v[196:197], v[174:175]
	v_pk_fma_f32 v[24:25], v[24:25], v[196:197], v[26:27]
	v_add_f32_e32 v206, v172, v173
	v_add_f32_e32 v24, v24, v25
	v_pk_mul_f32 v[26:27], v[164:165], v[196:197]
	v_add_f32_dpp v25, v206, v206 quad_perm:[1,0,3,2] row_mask:0xf bank_mask:0xf bound_ctrl:1
	v_add_f32_dpp v24, v24, v24 quad_perm:[1,0,3,2] row_mask:0xf bank_mask:0xf bound_ctrl:1
	v_pk_mul_f32 v[34:35], v[166:167], v[34:35]
	v_add_f32_dpp v25, v25, v25 quad_perm:[2,3,0,1] row_mask:0xf bank_mask:0xf bound_ctrl:1
	v_add_f32_dpp v24, v24, v24 quad_perm:[2,3,0,1] row_mask:0xf bank_mask:0xf bound_ctrl:1
	v_pk_fma_f32 v[34:35], v[170:171], v[198:199], v[34:35] op_sel_hi:[1,0,1]
	v_add_f32_dpp v25, v25, v25 row_ror:4 row_mask:0xf bank_mask:0xf bound_ctrl:1
	v_add_f32_dpp v164, v24, v24 row_ror:4 row_mask:0xf bank_mask:0xf bound_ctrl:1
	v_pk_fma_f32 v[26:27], v[168:169], v[198:199], v[26:27] op_sel_hi:[1,0,1]
	v_add_f32_dpp v24, v25, v25 row_ror:8 row_mask:0xf bank_mask:0xf bound_ctrl:1
	v_add_f32_dpp v25, v164, v164 row_ror:8 row_mask:0xf bank_mask:0xf bound_ctrl:1
	v_pk_fma_f32 v[196:197], v[176:177], v[24:25], v[26:27] op_sel_hi:[1,0,1]
	v_cndmask_b32_e64 v199, v199, v25, s[28:29]
	v_pk_fma_f32 v[34:35], v[178:179], v[24:25], v[34:35] op_sel_hi:[1,0,1]
	ds_read_b128 v[24:27], v28 offset:21504
	ds_read_b128 v[164:167], v28 offset:21760
	ds_read_b128 v[168:171], v28 offset:22016
	ds_read_b128 v[172:175], v28 offset:22528
	ds_read_b128 v[176:179], v28 offset:22784
	ds_read_b32 v198, v29 offset:22272
	s_waitcnt lgkmcnt(6)
	v_pk_mul_f32 v[190:191], v[190:191], v[34:35]
	v_pk_mul_f32 v[32:33], v[32:33], v[34:35]
	v_pk_fma_f32 v[188:189], v[188:189], v[196:197], v[190:191]
	v_pk_fma_f32 v[30:31], v[30:31], v[196:197], v[32:33]
	v_add_f32_e32 v206, v188, v189
	v_add_f32_e32 v30, v30, v31
	v_pk_mul_f32 v[32:33], v[180:181], v[196:197]
	v_add_f32_dpp v31, v206, v206 quad_perm:[1,0,3,2] row_mask:0xf bank_mask:0xf bound_ctrl:1
	v_add_f32_dpp v30, v30, v30 quad_perm:[1,0,3,2] row_mask:0xf bank_mask:0xf bound_ctrl:1
	v_pk_mul_f32 v[34:35], v[182:183], v[34:35]
	v_add_f32_dpp v31, v31, v31 quad_perm:[2,3,0,1] row_mask:0xf bank_mask:0xf bound_ctrl:1
	v_add_f32_dpp v30, v30, v30 quad_perm:[2,3,0,1] row_mask:0xf bank_mask:0xf bound_ctrl:1
	v_pk_fma_f32 v[34:35], v[186:187], v[200:201], v[34:35] op_sel_hi:[1,0,1]
	v_add_f32_dpp v31, v31, v31 row_ror:4 row_mask:0xf bank_mask:0xf bound_ctrl:1
	v_add_f32_dpp v180, v30, v30 row_ror:4 row_mask:0xf bank_mask:0xf bound_ctrl:1
	v_pk_fma_f32 v[32:33], v[184:185], v[200:201], v[32:33] op_sel_hi:[1,0,1]
	v_add_f32_dpp v30, v31, v31 row_ror:8 row_mask:0xf bank_mask:0xf bound_ctrl:1
	v_add_f32_dpp v31, v180, v180 row_ror:8 row_mask:0xf bank_mask:0xf bound_ctrl:1
	v_pk_fma_f32 v[196:197], v[192:193], v[30:31], v[32:33] op_sel_hi:[1,0,1]
	v_cndmask_b32_e64 v199, v199, v31, s[30:31]
	v_pk_fma_f32 v[34:35], v[194:195], v[30:31], v[34:35] op_sel_hi:[1,0,1]
	ds_read_b128 v[30:33], v28 offset:23040
	ds_read_b128 v[180:183], v28 offset:23296
	ds_read_b128 v[184:187], v28 offset:23552
	ds_read_b128 v[188:191], v28 offset:24064
	ds_read_b128 v[192:195], v28 offset:24320
	ds_read_b32 v200, v29 offset:23808
	s_waitcnt lgkmcnt(6)
	v_pk_mul_f32 v[174:175], v[174:175], v[34:35]
	v_pk_mul_f32 v[162:163], v[162:163], v[34:35]
	v_pk_fma_f32 v[172:173], v[172:173], v[196:197], v[174:175]
	v_pk_fma_f32 v[160:161], v[160:161], v[196:197], v[162:163]
	v_add_f32_e32 v206, v172, v173
	v_add_f32_e32 v160, v160, v161
	v_pk_mul_f32 v[162:163], v[164:165], v[196:197]
	v_add_f32_dpp v161, v206, v206 quad_perm:[1,0,3,2] row_mask:0xf bank_mask:0xf bound_ctrl:1
	v_add_f32_dpp v160, v160, v160 quad_perm:[1,0,3,2] row_mask:0xf bank_mask:0xf bound_ctrl:1
	v_pk_mul_f32 v[34:35], v[166:167], v[34:35]
	v_add_f32_dpp v161, v161, v161 quad_perm:[2,3,0,1] row_mask:0xf bank_mask:0xf bound_ctrl:1
	v_add_f32_dpp v160, v160, v160 quad_perm:[2,3,0,1] row_mask:0xf bank_mask:0xf bound_ctrl:1
	v_pk_fma_f32 v[34:35], v[170:171], v[198:199], v[34:35] op_sel_hi:[1,0,1]
	v_add_f32_dpp v161, v161, v161 row_ror:4 row_mask:0xf bank_mask:0xf bound_ctrl:1
	v_add_f32_dpp v164, v160, v160 row_ror:4 row_mask:0xf bank_mask:0xf bound_ctrl:1
	v_pk_fma_f32 v[162:163], v[168:169], v[198:199], v[162:163] op_sel_hi:[1,0,1]
	v_add_f32_dpp v160, v161, v161 row_ror:8 row_mask:0xf bank_mask:0xf bound_ctrl:1
	v_add_f32_dpp v161, v164, v164 row_ror:8 row_mask:0xf bank_mask:0xf bound_ctrl:1
	v_pk_fma_f32 v[196:197], v[176:177], v[160:161], v[162:163] op_sel_hi:[1,0,1]
	v_cndmask_b32_e64 v199, v199, v161, s[34:35]
	v_pk_fma_f32 v[34:35], v[178:179], v[160:161], v[34:35] op_sel_hi:[1,0,1]
	ds_read_b128 v[160:163], v28 offset:24576
	ds_read_b128 v[164:167], v28 offset:24832
	ds_read_b128 v[168:171], v28 offset:25088
	ds_read_b128 v[172:175], v28 offset:25600
	ds_read_b128 v[176:179], v28 offset:25856
	ds_read_b32 v198, v29 offset:25344
	s_waitcnt lgkmcnt(6)
; #define LAS __attribute__((address_space(3)))
; __device__ __forceinline__ void rwkv_scan_prompt(const Params& p, LAS unsigned char* lds, int bh, int rq) {
;     ...
;             for (int tk = 0; tk < TC; ++tk) {
;                 f32x4 nr4 = r4, nd4 = d4, nk4 = k4, na4 = a4, nb4 = b4; float nvv = vv;
;                 if (tk < TC - 1) {
;                     const LAS float* o = ob + (tk + 1) * 6 * 64;
;                     nr4 = *(const LAS f32x4*)(o + cg_ * 4); nd4 = *(const LAS f32x4*)(o + 64 + cg_ * 4); nk4 = *(const LAS f32x4*)(o + 128 + cg_ * 4);
;                     na4 = *(const LAS f32x4*)(o + 256 + cg_ * 4); nb4 = *(const LAS f32x4*)(o + 320 + cg_ * 4);
;                     nvv = o[192 + rq * 16 + rloc];
;                 }
;                 __builtin_amdgcn_sched_barrier(0);
;                 typedef float f32x2_ __attribute__((ext_vector_type(2)));
;                 f32x2_ ta = (f32x2_){S[0], S[1]} * (f32x2_){a4[0], a4[1]}; ta = (f32x2_){S[2], S[3]} * (f32x2_){a4[2], a4[3]} + ta;
;                 f32x2_ ty = (f32x2_){S[0], S[1]} * (f32x2_){rp[0], rp[1]}; ty = (f32x2_){S[2], S[3]} * (f32x2_){rp[2], rp[3]} + ty;
;                 const f32x4 T = S * d4 + vv * k4;
;                 float sa = ta[0] + ta[1];
;                 float yp = ty[0] + ty[1];
;                 sa = dpp_add<0xB1>(sa); yp = dpp_add<0xB1>(yp);
;                 sa = dpp_add<0x4E>(sa); yp = dpp_add<0x4E>(yp);
;                 sa = dpp_add<0x124>(sa); yp = dpp_add<0x124>(yp);
;                 sa = dpp_add<0x128>(sa); yp = dpp_add<0x128>(yp);
;                 if (tk > 0) yk[(tk - 1) >> 4] = (cg_ == ((tk - 1) & 15)) ? yp : yk[(tk - 1) >> 4];
;                 S = sa * b4 + T;
;                 rp = r4;
;                 r4 = nr4; d4 = nd4; k4 = nk4; a4 = na4; b4 = nb4; vv = nvv;
	v_pk_mul_f32 v[190:191], v[190:191], v[34:35]
	v_pk_mul_f32 v[26:27], v[26:27], v[34:35]
	v_pk_fma_f32 v[188:189], v[188:189], v[196:197], v[190:191]
	v_pk_fma_f32 v[24:25], v[24:25], v[196:197], v[26:27]
	v_add_f32_e32 v206, v188, v189
	v_add_f32_e32 v24, v24, v25
	v_pk_mul_f32 v[26:27], v[180:181], v[196:197]
	v_add_f32_dpp v25, v206, v206 quad_perm:[1,0,3,2] row_mask:0xf bank_mask:0xf bound_ctrl:1
	v_add_f32_dpp v24, v24, v24 quad_perm:[1,0,3,2] row_mask:0xf bank_mask:0xf bound_ctrl:1
	v_pk_mul_f32 v[34:35], v[182:183], v[34:35]
	v_add_f32_dpp v25, v25, v25 quad_perm:[2,3,0,1] row_mask:0xf bank_mask:0xf bound_ctrl:1
	v_add_f32_dpp v24, v24, v24 quad_perm:[2,3,0,1] row_mask:0xf bank_mask:0xf bound_ctrl:1
	v_pk_fma_f32 v[34:35], v[186:187], v[200:201], v[34:35] op_sel_hi:[1,0,1]
	v_add_f32_dpp v25, v25, v25 row_ror:4 row_mask:0xf bank_mask:0xf bound_ctrl:1
	v_add_f32_dpp v180, v24, v24 row_ror:4 row_mask:0xf bank_mask:0xf bound_ctrl:1
	v_pk_fma_f32 v[26:27], v[184:185], v[200:201], v[26:27] op_sel_hi:[1,0,1]
	v_add_f32_dpp v24, v25, v25 row_ror:8 row_mask:0xf bank_mask:0xf bound_ctrl:1
	v_add_f32_dpp v25, v180, v180 row_ror:8 row_mask:0xf bank_mask:0xf bound_ctrl:1
	v_pk_fma_f32 v[196:197], v[192:193], v[24:25], v[26:27] op_sel_hi:[1,0,1]
	v_cndmask_b32_e64 v199, v199, v25, s[36:37]
	v_pk_fma_f32 v[34:35], v[194:195], v[24:25], v[34:35] op_sel_hi:[1,0,1]
	ds_read_b128 v[24:27], v28 offset:26112
	ds_read_b128 v[180:183], v28 offset:26368
	ds_read_b128 v[184:187], v28 offset:26624
	ds_read_b128 v[188:191], v28 offset:27136
	ds_read_b128 v[192:195], v28 offset:27392
	ds_read_b32 v200, v29 offset:26880
	s_waitcnt lgkmcnt(6)
	v_pk_mul_f32 v[174:175], v[174:175], v[34:35]
	v_pk_mul_f32 v[32:33], v[32:33], v[34:35]
	v_pk_fma_f32 v[172:173], v[172:173], v[196:197], v[174:175]
	v_pk_fma_f32 v[30:31], v[30:31], v[196:197], v[32:33]
	v_add_f32_e32 v206, v172, v173
	v_add_f32_e32 v30, v30, v31
	v_pk_mul_f32 v[32:33], v[164:165], v[196:197]
	v_add_f32_dpp v31, v206, v206 quad_perm:[1,0,3,2] row_mask:0xf bank_mask:0xf bound_ctrl:1
	v_add_f32_dpp v30, v30, v30 quad_perm:[1,0,3,2] row_mask:0xf bank_mask:0xf bound_ctrl:1
	v_pk_mul_f32 v[34:35], v[166:167], v[34:35]
	v_add_f32_dpp v31, v31, v31 quad_perm:[2,3,0,1] row_mask:0xf bank_mask:0xf bound_ctrl:1
	v_add_f32_dpp v30, v30, v30 quad_perm:[2,3,0,1] row_mask:0xf bank_mask:0xf bound_ctrl:1
	v_pk_fma_f32 v[34:35], v[170:171], v[198:199], v[34:35] op_sel_hi:[1,0,1]
	v_add_f32_dpp v31, v31, v31 row_ror:4 row_mask:0xf bank_mask:0xf bound_ctrl:1
	v_add_f32_dpp v30, v30, v30 row_ror:4 row_mask:0xf bank_mask:0xf bound_ctrl:1
	v_pk_fma_f32 v[32:33], v[168:169], v[198:199], v[32:33] op_sel_hi:[1,0,1]
	v_add_f32_dpp v164, v31, v31 row_ror:8 row_mask:0xf bank_mask:0xf bound_ctrl:1
	v_add_f32_dpp v30, v30, v30 row_ror:8 row_mask:0xf bank_mask:0xf bound_ctrl:1
	v_pk_fma_f32 v[196:197], v[176:177], v[164:165], v[32:33] op_sel_hi:[1,0,1]
	v_cndmask_b32_e64 v30, v199, v30, s[4:5]
	v_pk_fma_f32 v[198:199], v[178:179], v[164:165], v[34:35] op_sel_hi:[1,0,1]
	ds_read_b128 v[32:35], v28 offset:27648
	ds_read_b128 v[164:167], v28 offset:27904
	ds_read_b128 v[168:171], v28 offset:28160
	ds_read_b128 v[172:175], v28 offset:28672
	ds_read_b128 v[176:179], v28 offset:28928
	ds_read_b32 v202, v29 offset:28416
	s_waitcnt lgkmcnt(6)
	v_pk_mul_f32 v[190:191], v[190:191], v[198:199]
	v_pk_mul_f32 v[162:163], v[162:163], v[198:199]
	v_pk_fma_f32 v[188:189], v[188:189], v[196:197], v[190:191]
	v_pk_fma_f32 v[160:161], v[160:161], v[196:197], v[162:163]
	v_add_f32_e32 v31, v188, v189
	v_add_f32_e32 v160, v160, v161
	v_pk_mul_f32 v[162:163], v[180:181], v[196:197]
	v_add_f32_dpp v31, v31, v31 quad_perm:[1,0,3,2] row_mask:0xf bank_mask:0xf bound_ctrl:1
	v_add_f32_dpp v160, v160, v160 quad_perm:[1,0,3,2] row_mask:0xf bank_mask:0xf bound_ctrl:1
	v_pk_mul_f32 v[180:181], v[182:183], v[198:199]
	v_add_f32_dpp v31, v31, v31 quad_perm:[2,3,0,1] row_mask:0xf bank_mask:0xf bound_ctrl:1
	v_add_f32_dpp v160, v160, v160 quad_perm:[2,3,0,1] row_mask:0xf bank_mask:0xf bound_ctrl:1
	v_pk_fma_f32 v[180:181], v[186:187], v[200:201], v[180:181] op_sel_hi:[1,0,1]
	v_add_f32_dpp v31, v31, v31 row_ror:4 row_mask:0xf bank_mask:0xf bound_ctrl:1
	v_pk_fma_f32 v[162:163], v[184:185], v[200:201], v[162:163] op_sel_hi:[1,0,1]
	v_add_f32_dpp v161, v160, v160 row_ror:4 row_mask:0xf bank_mask:0xf bound_ctrl:1
	v_add_f32_dpp v160, v31, v31 row_ror:8 row_mask:0xf bank_mask:0xf bound_ctrl:1
	v_pk_fma_f32 v[196:197], v[192:193], v[160:161], v[162:163] op_sel_hi:[1,0,1]
	v_add_f32_dpp v31, v161, v161 row_ror:8 row_mask:0xf bank_mask:0xf bound_ctrl:1
	v_pk_fma_f32 v[198:199], v[194:195], v[160:161], v[180:181] op_sel_hi:[1,0,1]
	ds_read_b128 v[160:163], v28 offset:29184
	ds_read_b128 v[180:183], v28 offset:29440
	ds_read_b128 v[184:187], v28 offset:29696
	ds_read_b128 v[188:191], v28 offset:30208
	ds_read_b128 v[192:195], v28 offset:30464
	ds_read_b32 v200, v29 offset:29952
	v_cndmask_b32_e64 v31, 0, v31, s[6:7]
	s_waitcnt lgkmcnt(6)
; #define LAS __attribute__((address_space(3)))
; __device__ __forceinline__ void rwkv_scan_prompt(const Params& p, LAS unsigned char* lds, int bh, int rq) {
;     ...
;             for (int tk = 0; tk < TC; ++tk) {
;                 f32x4 nr4 = r4, nd4 = d4, nk4 = k4, na4 = a4, nb4 = b4; float nvv = vv;
;                 if (tk < TC - 1) {
;                     const LAS float* o = ob + (tk + 1) * 6 * 64;
;                     nr4 = *(const LAS f32x4*)(o + cg_ * 4); nd4 = *(const LAS f32x4*)(o + 64 + cg_ * 4); nk4 = *(const LAS f32x4*)(o + 128 + cg_ * 4);
;                     na4 = *(const LAS f32x4*)(o + 256 + cg_ * 4); nb4 = *(const LAS f32x4*)(o + 320 + cg_ * 4);
;                     nvv = o[192 + rq * 16 + rloc];
;                 }
;                 __builtin_amdgcn_sched_barrier(0);
;                 typedef float f32x2_ __attribute__((ext_vector_type(2)));
;                 f32x2_ ta = (f32x2_){S[0], S[1]} * (f32x2_){a4[0], a4[1]}; ta = (f32x2_){S[2], S[3]} * (f32x2_){a4[2], a4[3]} + ta;
;                 f32x2_ ty = (f32x2_){S[0], S[1]} * (f32x2_){rp[0], rp[1]}; ty = (f32x2_){S[2], S[3]} * (f32x2_){rp[2], rp[3]} + ty;
;                 const f32x4 T = S * d4 + vv * k4;
;                 float sa = ta[0] + ta[1];
;                 float yp = ty[0] + ty[1];
;                 sa = dpp_add<0xB1>(sa); yp = dpp_add<0xB1>(yp);
;                 sa = dpp_add<0x4E>(sa); yp = dpp_add<0x4E>(yp);
;                 sa = dpp_add<0x124>(sa); yp = dpp_add<0x124>(yp);
;                 sa = dpp_add<0x128>(sa); yp = dpp_add<0x128>(yp);
;                 if (tk > 0) yk[(tk - 1) >> 4] = (cg_ == ((tk - 1) & 15)) ? yp : yk[(tk - 1) >> 4];
;                 S = sa * b4 + T;
;                 rp = r4;
;                 r4 = nr4; d4 = nd4; k4 = nk4; a4 = na4; b4 = nb4; vv = nvv;
	v_pk_mul_f32 v[174:175], v[174:175], v[198:199]
	v_pk_mul_f32 v[26:27], v[26:27], v[198:199]
	v_pk_fma_f32 v[172:173], v[172:173], v[196:197], v[174:175]
	v_pk_fma_f32 v[24:25], v[24:25], v[196:197], v[26:27]
	v_add_f32_e32 v206, v172, v173
	v_add_f32_e32 v24, v24, v25
	v_pk_mul_f32 v[26:27], v[164:165], v[196:197]
	v_add_f32_dpp v25, v206, v206 quad_perm:[1,0,3,2] row_mask:0xf bank_mask:0xf bound_ctrl:1
	v_add_f32_dpp v24, v24, v24 quad_perm:[1,0,3,2] row_mask:0xf bank_mask:0xf bound_ctrl:1
	v_pk_mul_f32 v[164:165], v[166:167], v[198:199]
	v_add_f32_dpp v25, v25, v25 quad_perm:[2,3,0,1] row_mask:0xf bank_mask:0xf bound_ctrl:1
	v_add_f32_dpp v24, v24, v24 quad_perm:[2,3,0,1] row_mask:0xf bank_mask:0xf bound_ctrl:1
	v_pk_fma_f32 v[164:165], v[170:171], v[202:203], v[164:165] op_sel_hi:[1,0,1]
	v_add_f32_dpp v25, v25, v25 row_ror:4 row_mask:0xf bank_mask:0xf bound_ctrl:1
	v_add_f32_dpp v166, v24, v24 row_ror:4 row_mask:0xf bank_mask:0xf bound_ctrl:1
	v_pk_fma_f32 v[26:27], v[168:169], v[202:203], v[26:27] op_sel_hi:[1,0,1]
	v_add_f32_dpp v24, v25, v25 row_ror:8 row_mask:0xf bank_mask:0xf bound_ctrl:1
	v_add_f32_dpp v25, v166, v166 row_ror:8 row_mask:0xf bank_mask:0xf bound_ctrl:1
	v_pk_fma_f32 v[196:197], v[176:177], v[24:25], v[26:27] op_sel_hi:[1,0,1]
	v_cndmask_b32_e64 v31, v31, v25, s[8:9]
	v_pk_fma_f32 v[198:199], v[178:179], v[24:25], v[164:165] op_sel_hi:[1,0,1]
	ds_read_b128 v[24:27], v28 offset:30720
	ds_read_b128 v[164:167], v28 offset:30976
	ds_read_b128 v[168:171], v28 offset:31232
	ds_read_b128 v[172:175], v28 offset:31744
	ds_read_b128 v[176:179], v28 offset:32000
	ds_read_b32 v202, v29 offset:31488
	s_waitcnt lgkmcnt(6)
	v_pk_mul_f32 v[190:191], v[190:191], v[198:199]
	v_pk_mul_f32 v[34:35], v[34:35], v[198:199]
	v_pk_fma_f32 v[188:189], v[188:189], v[196:197], v[190:191]
	v_pk_fma_f32 v[32:33], v[32:33], v[196:197], v[34:35]
	v_add_f32_e32 v206, v188, v189
	v_add_f32_e32 v32, v32, v33
	v_pk_mul_f32 v[34:35], v[180:181], v[196:197]
	v_add_f32_dpp v33, v206, v206 quad_perm:[1,0,3,2] row_mask:0xf bank_mask:0xf bound_ctrl:1
	v_add_f32_dpp v32, v32, v32 quad_perm:[1,0,3,2] row_mask:0xf bank_mask:0xf bound_ctrl:1
	v_pk_mul_f32 v[180:181], v[182:183], v[198:199]
	v_add_f32_dpp v33, v33, v33 quad_perm:[2,3,0,1] row_mask:0xf bank_mask:0xf bound_ctrl:1
	v_add_f32_dpp v32, v32, v32 quad_perm:[2,3,0,1] row_mask:0xf bank_mask:0xf bound_ctrl:1
	v_pk_fma_f32 v[180:181], v[186:187], v[200:201], v[180:181] op_sel_hi:[1,0,1]
	v_add_f32_dpp v33, v33, v33 row_ror:4 row_mask:0xf bank_mask:0xf bound_ctrl:1
	v_add_f32_dpp v182, v32, v32 row_ror:4 row_mask:0xf bank_mask:0xf bound_ctrl:1
	v_pk_fma_f32 v[34:35], v[184:185], v[200:201], v[34:35] op_sel_hi:[1,0,1]
	v_add_f32_dpp v32, v33, v33 row_ror:8 row_mask:0xf bank_mask:0xf bound_ctrl:1
	v_add_f32_dpp v33, v182, v182 row_ror:8 row_mask:0xf bank_mask:0xf bound_ctrl:1
	v_pk_fma_f32 v[196:197], v[192:193], v[32:33], v[34:35] op_sel_hi:[1,0,1]
	v_cndmask_b32_e64 v31, v31, v33, s[10:11]
	v_pk_fma_f32 v[198:199], v[194:195], v[32:33], v[180:181] op_sel_hi:[1,0,1]
	ds_read_b128 v[32:35], v28 offset:32256
	ds_read_b128 v[180:183], v28 offset:32512
	ds_read_b128 v[184:187], v28 offset:32768
	ds_read_b128 v[188:191], v28 offset:33280
	ds_read_b128 v[192:195], v28 offset:33536
	ds_read_b32 v200, v29 offset:33024
	s_waitcnt lgkmcnt(6)
	v_pk_mul_f32 v[174:175], v[174:175], v[198:199]
	v_pk_mul_f32 v[162:163], v[162:163], v[198:199]
	v_pk_fma_f32 v[172:173], v[172:173], v[196:197], v[174:175]
	v_pk_fma_f32 v[160:161], v[160:161], v[196:197], v[162:163]
	v_add_f32_e32 v206, v172, v173
	v_add_f32_e32 v160, v160, v161
	v_pk_mul_f32 v[162:163], v[164:165], v[196:197]
	v_add_f32_dpp v161, v206, v206 quad_perm:[1,0,3,2] row_mask:0xf bank_mask:0xf bound_ctrl:1
	v_add_f32_dpp v160, v160, v160 quad_perm:[1,0,3,2] row_mask:0xf bank_mask:0xf bound_ctrl:1
	v_pk_mul_f32 v[164:165], v[166:167], v[198:199]
	v_add_f32_dpp v161, v161, v161 quad_perm:[2,3,0,1] row_mask:0xf bank_mask:0xf bound_ctrl:1
	v_add_f32_dpp v160, v160, v160 quad_perm:[2,3,0,1] row_mask:0xf bank_mask:0xf bound_ctrl:1
	v_pk_fma_f32 v[164:165], v[170:171], v[202:203], v[164:165] op_sel_hi:[1,0,1]
	v_add_f32_dpp v161, v161, v161 row_ror:4 row_mask:0xf bank_mask:0xf bound_ctrl:1
	v_add_f32_dpp v166, v160, v160 row_ror:4 row_mask:0xf bank_mask:0xf bound_ctrl:1
	v_pk_fma_f32 v[162:163], v[168:169], v[202:203], v[162:163] op_sel_hi:[1,0,1]
	v_add_f32_dpp v160, v161, v161 row_ror:8 row_mask:0xf bank_mask:0xf bound_ctrl:1
	v_add_f32_dpp v161, v166, v166 row_ror:8 row_mask:0xf bank_mask:0xf bound_ctrl:1
	v_pk_fma_f32 v[196:197], v[176:177], v[160:161], v[162:163] op_sel_hi:[1,0,1]
	v_cndmask_b32_e64 v31, v31, v161, s[12:13]
	v_pk_fma_f32 v[198:199], v[178:179], v[160:161], v[164:165] op_sel_hi:[1,0,1]
	ds_read_b128 v[160:163], v28 offset:33792
	ds_read_b128 v[164:167], v28 offset:34048
	ds_read_b128 v[168:171], v28 offset:34304
	ds_read_b128 v[172:175], v28 offset:34816
	ds_read_b128 v[176:179], v28 offset:35072
	ds_read_b32 v202, v29 offset:34560
	s_waitcnt lgkmcnt(6)
; #define LAS __attribute__((address_space(3)))
; __device__ __forceinline__ void rwkv_scan_prompt(const Params& p, LAS unsigned char* lds, int bh, int rq) {
;     ...
;             for (int tk = 0; tk < TC; ++tk) {
;                 f32x4 nr4 = r4, nd4 = d4, nk4 = k4, na4 = a4, nb4 = b4; float nvv = vv;
;                 if (tk < TC - 1) {
;                     const LAS float* o = ob + (tk + 1) * 6 * 64;
;                     nr4 = *(const LAS f32x4*)(o + cg_ * 4); nd4 = *(const LAS f32x4*)(o + 64 + cg_ * 4); nk4 = *(const LAS f32x4*)(o + 128 + cg_ * 4);
;                     na4 = *(const LAS f32x4*)(o + 256 + cg_ * 4); nb4 = *(const LAS f32x4*)(o + 320 + cg_ * 4);
;                     nvv = o[192 + rq * 16 + rloc];
;                 }
;                 __builtin_amdgcn_sched_barrier(0);
;                 typedef float f32x2_ __attribute__((ext_vector_type(2)));
;                 f32x2_ ta = (f32x2_){S[0], S[1]} * (f32x2_){a4[0], a4[1]}; ta = (f32x2_){S[2], S[3]} * (f32x2_){a4[2], a4[3]} + ta;
;                 f32x2_ ty = (f32x2_){S[0], S[1]} * (f32x2_){rp[0], rp[1]}; ty = (f32x2_){S[2], S[3]} * (f32x2_){rp[2], rp[3]} + ty;
;                 const f32x4 T = S * d4 + vv * k4;
;                 float sa = ta[0] + ta[1];
;                 float yp = ty[0] + ty[1];
;                 sa = dpp_add<0xB1>(sa); yp = dpp_add<0xB1>(yp);
;                 sa = dpp_add<0x4E>(sa); yp = dpp_add<0x4E>(yp);
;                 sa = dpp_add<0x124>(sa); yp = dpp_add<0x124>(yp);
;                 sa = dpp_add<0x128>(sa); yp = dpp_add<0x128>(yp);
;                 if (tk > 0) yk[(tk - 1) >> 4] = (cg_ == ((tk - 1) & 15)) ? yp : yk[(tk - 1) >> 4];
;                 S = sa * b4 + T;
;                 rp = r4;
;                 r4 = nr4; d4 = nd4; k4 = nk4; a4 = na4; b4 = nb4; vv = nvv;
	v_pk_mul_f32 v[190:191], v[190:191], v[198:199]
	v_pk_mul_f32 v[26:27], v[26:27], v[198:199]
	v_pk_fma_f32 v[188:189], v[188:189], v[196:197], v[190:191]
	v_pk_fma_f32 v[24:25], v[24:25], v[196:197], v[26:27]
	v_add_f32_e32 v206, v188, v189
	v_add_f32_e32 v24, v24, v25
	v_pk_mul_f32 v[26:27], v[180:181], v[196:197]
	v_add_f32_dpp v25, v206, v206 quad_perm:[1,0,3,2] row_mask:0xf bank_mask:0xf bound_ctrl:1
	v_add_f32_dpp v24, v24, v24 quad_perm:[1,0,3,2] row_mask:0xf bank_mask:0xf bound_ctrl:1
	v_pk_mul_f32 v[180:181], v[182:183], v[198:199]
	v_add_f32_dpp v25, v25, v25 quad_perm:[2,3,0,1] row_mask:0xf bank_mask:0xf bound_ctrl:1
	v_add_f32_dpp v24, v24, v24 quad_perm:[2,3,0,1] row_mask:0xf bank_mask:0xf bound_ctrl:1
	v_pk_fma_f32 v[180:181], v[186:187], v[200:201], v[180:181] op_sel_hi:[1,0,1]
	v_add_f32_dpp v25, v25, v25 row_ror:4 row_mask:0xf bank_mask:0xf bound_ctrl:1
	v_add_f32_dpp v182, v24, v24 row_ror:4 row_mask:0xf bank_mask:0xf bound_ctrl:1
	v_pk_fma_f32 v[26:27], v[184:185], v[200:201], v[26:27] op_sel_hi:[1,0,1]
	v_add_f32_dpp v24, v25, v25 row_ror:8 row_mask:0xf bank_mask:0xf bound_ctrl:1
	v_add_f32_dpp v25, v182, v182 row_ror:8 row_mask:0xf bank_mask:0xf bound_ctrl:1
	v_pk_fma_f32 v[196:197], v[192:193], v[24:25], v[26:27] op_sel_hi:[1,0,1]
	v_cndmask_b32_e64 v31, v31, v25, s[14:15]
	v_pk_fma_f32 v[198:199], v[194:195], v[24:25], v[180:181] op_sel_hi:[1,0,1]
	ds_read_b128 v[24:27], v28 offset:35328
	ds_read_b128 v[180:183], v28 offset:35584
	ds_read_b128 v[184:187], v28 offset:35840
	ds_read_b128 v[188:191], v28 offset:36352
	ds_read_b128 v[192:195], v28 offset:36608
	ds_read_b32 v200, v29 offset:36096
	s_waitcnt lgkmcnt(6)
	v_pk_mul_f32 v[174:175], v[174:175], v[198:199]
	v_pk_mul_f32 v[34:35], v[34:35], v[198:199]
	v_pk_fma_f32 v[172:173], v[172:173], v[196:197], v[174:175]
	v_pk_fma_f32 v[32:33], v[32:33], v[196:197], v[34:35]
	v_add_f32_e32 v206, v172, v173
	v_add_f32_e32 v32, v32, v33
	v_pk_mul_f32 v[34:35], v[164:165], v[196:197]
	v_add_f32_dpp v33, v206, v206 quad_perm:[1,0,3,2] row_mask:0xf bank_mask:0xf bound_ctrl:1
	v_add_f32_dpp v32, v32, v32 quad_perm:[1,0,3,2] row_mask:0xf bank_mask:0xf bound_ctrl:1
	v_pk_mul_f32 v[164:165], v[166:167], v[198:199]
	v_add_f32_dpp v33, v33, v33 quad_perm:[2,3,0,1] row_mask:0xf bank_mask:0xf bound_ctrl:1
	v_add_f32_dpp v32, v32, v32 quad_perm:[2,3,0,1] row_mask:0xf bank_mask:0xf bound_ctrl:1
	v_pk_fma_f32 v[164:165], v[170:171], v[202:203], v[164:165] op_sel_hi:[1,0,1]
	v_add_f32_dpp v33, v33, v33 row_ror:4 row_mask:0xf bank_mask:0xf bound_ctrl:1
	v_add_f32_dpp v166, v32, v32 row_ror:4 row_mask:0xf bank_mask:0xf bound_ctrl:1
	v_pk_fma_f32 v[34:35], v[168:169], v[202:203], v[34:35] op_sel_hi:[1,0,1]
	v_add_f32_dpp v32, v33, v33 row_ror:8 row_mask:0xf bank_mask:0xf bound_ctrl:1
	v_add_f32_dpp v33, v166, v166 row_ror:8 row_mask:0xf bank_mask:0xf bound_ctrl:1
	v_pk_fma_f32 v[196:197], v[176:177], v[32:33], v[34:35] op_sel_hi:[1,0,1]
	v_cndmask_b32_e64 v31, v31, v33, s[16:17]
	v_pk_fma_f32 v[198:199], v[178:179], v[32:33], v[164:165] op_sel_hi:[1,0,1]
	ds_read_b128 v[32:35], v28 offset:36864
	ds_read_b128 v[164:167], v28 offset:37120
	ds_read_b128 v[168:171], v28 offset:37376
	ds_read_b128 v[172:175], v28 offset:37888
	ds_read_b128 v[176:179], v28 offset:38144
	ds_read_b32 v202, v29 offset:37632
	s_waitcnt lgkmcnt(6)
	v_pk_mul_f32 v[190:191], v[190:191], v[198:199]
	v_pk_mul_f32 v[162:163], v[162:163], v[198:199]
	v_pk_fma_f32 v[188:189], v[188:189], v[196:197], v[190:191]
	v_pk_fma_f32 v[160:161], v[160:161], v[196:197], v[162:163]
	v_add_f32_e32 v206, v188, v189
	v_add_f32_e32 v160, v160, v161
	v_pk_mul_f32 v[162:163], v[180:181], v[196:197]
	v_add_f32_dpp v161, v206, v206 quad_perm:[1,0,3,2] row_mask:0xf bank_mask:0xf bound_ctrl:1
	v_add_f32_dpp v160, v160, v160 quad_perm:[1,0,3,2] row_mask:0xf bank_mask:0xf bound_ctrl:1
	v_pk_mul_f32 v[180:181], v[182:183], v[198:199]
	v_add_f32_dpp v161, v161, v161 quad_perm:[2,3,0,1] row_mask:0xf bank_mask:0xf bound_ctrl:1
	v_add_f32_dpp v160, v160, v160 quad_perm:[2,3,0,1] row_mask:0xf bank_mask:0xf bound_ctrl:1
	v_pk_fma_f32 v[180:181], v[186:187], v[200:201], v[180:181] op_sel_hi:[1,0,1]
	v_add_f32_dpp v161, v161, v161 row_ror:4 row_mask:0xf bank_mask:0xf bound_ctrl:1
	v_add_f32_dpp v182, v160, v160 row_ror:4 row_mask:0xf bank_mask:0xf bound_ctrl:1
	v_pk_fma_f32 v[162:163], v[184:185], v[200:201], v[162:163] op_sel_hi:[1,0,1]
	v_add_f32_dpp v160, v161, v161 row_ror:8 row_mask:0xf bank_mask:0xf bound_ctrl:1
	v_add_f32_dpp v161, v182, v182 row_ror:8 row_mask:0xf bank_mask:0xf bound_ctrl:1
	v_pk_fma_f32 v[196:197], v[192:193], v[160:161], v[162:163] op_sel_hi:[1,0,1]
	v_cndmask_b32_e64 v31, v31, v161, s[18:19]
	v_pk_fma_f32 v[198:199], v[194:195], v[160:161], v[180:181] op_sel_hi:[1,0,1]
	ds_read_b128 v[160:163], v28 offset:38400
	ds_read_b128 v[180:183], v28 offset:38656
	ds_read_b128 v[184:187], v28 offset:38912
	ds_read_b128 v[188:191], v28 offset:39424
	ds_read_b128 v[192:195], v28 offset:39680
	ds_read_b32 v200, v29 offset:39168
	s_waitcnt lgkmcnt(6)
; #define LAS __attribute__((address_space(3)))
; __device__ __forceinline__ void rwkv_scan_prompt(const Params& p, LAS unsigned char* lds, int bh, int rq) {
;     ...
;             for (int tk = 0; tk < TC; ++tk) {
;                 f32x4 nr4 = r4, nd4 = d4, nk4 = k4, na4 = a4, nb4 = b4; float nvv = vv;
;                 if (tk < TC - 1) {
;                     const LAS float* o = ob + (tk + 1) * 6 * 64;
;                     nr4 = *(const LAS f32x4*)(o + cg_ * 4); nd4 = *(const LAS f32x4*)(o + 64 + cg_ * 4); nk4 = *(const LAS f32x4*)(o + 128 + cg_ * 4);
;                     na4 = *(const LAS f32x4*)(o + 256 + cg_ * 4); nb4 = *(const LAS f32x4*)(o + 320 + cg_ * 4);
;                     nvv = o[192 + rq * 16 + rloc];
;                 }
;                 __builtin_amdgcn_sched_barrier(0);
;                 typedef float f32x2_ __attribute__((ext_vector_type(2)));
;                 f32x2_ ta = (f32x2_){S[0], S[1]} * (f32x2_){a4[0], a4[1]}; ta = (f32x2_){S[2], S[3]} * (f32x2_){a4[2], a4[3]} + ta;
;                 f32x2_ ty = (f32x2_){S[0], S[1]} * (f32x2_){rp[0], rp[1]}; ty = (f32x2_){S[2], S[3]} * (f32x2_){rp[2], rp[3]} + ty;
;                 const f32x4 T = S * d4 + vv * k4;
;                 float sa = ta[0] + ta[1];
;                 float yp = ty[0] + ty[1];
;                 sa = dpp_add<0xB1>(sa); yp = dpp_add<0xB1>(yp);
;                 sa = dpp_add<0x4E>(sa); yp = dpp_add<0x4E>(yp);
;                 sa = dpp_add<0x124>(sa); yp = dpp_add<0x124>(yp);
;                 sa = dpp_add<0x128>(sa); yp = dpp_add<0x128>(yp);
;                 if (tk > 0) yk[(tk - 1) >> 4] = (cg_ == ((tk - 1) & 15)) ? yp : yk[(tk - 1) >> 4];
;                 S = sa * b4 + T;
;                 rp = r4;
;                 r4 = nr4; d4 = nd4; k4 = nk4; a4 = na4; b4 = nb4; vv = nvv;
	v_pk_mul_f32 v[174:175], v[174:175], v[198:199]
	v_pk_mul_f32 v[26:27], v[26:27], v[198:199]
	v_pk_fma_f32 v[172:173], v[172:173], v[196:197], v[174:175]
	v_pk_fma_f32 v[24:25], v[24:25], v[196:197], v[26:27]
	v_add_f32_e32 v206, v172, v173
	v_add_f32_e32 v24, v24, v25
	v_pk_mul_f32 v[26:27], v[164:165], v[196:197]
	v_add_f32_dpp v25, v206, v206 quad_perm:[1,0,3,2] row_mask:0xf bank_mask:0xf bound_ctrl:1
	v_add_f32_dpp v24, v24, v24 quad_perm:[1,0,3,2] row_mask:0xf bank_mask:0xf bound_ctrl:1
	v_pk_mul_f32 v[164:165], v[166:167], v[198:199]
	v_add_f32_dpp v25, v25, v25 quad_perm:[2,3,0,1] row_mask:0xf bank_mask:0xf bound_ctrl:1
	v_add_f32_dpp v24, v24, v24 quad_perm:[2,3,0,1] row_mask:0xf bank_mask:0xf bound_ctrl:1
	v_pk_fma_f32 v[164:165], v[170:171], v[202:203], v[164:165] op_sel_hi:[1,0,1]
	v_add_f32_dpp v25, v25, v25 row_ror:4 row_mask:0xf bank_mask:0xf bound_ctrl:1
	v_add_f32_dpp v166, v24, v24 row_ror:4 row_mask:0xf bank_mask:0xf bound_ctrl:1
	v_pk_fma_f32 v[26:27], v[168:169], v[202:203], v[26:27] op_sel_hi:[1,0,1]
	v_add_f32_dpp v24, v25, v25 row_ror:8 row_mask:0xf bank_mask:0xf bound_ctrl:1
	v_add_f32_dpp v25, v166, v166 row_ror:8 row_mask:0xf bank_mask:0xf bound_ctrl:1
	v_pk_fma_f32 v[196:197], v[176:177], v[24:25], v[26:27] op_sel_hi:[1,0,1]
	v_cndmask_b32_e64 v31, v31, v25, s[20:21]
	v_pk_fma_f32 v[198:199], v[178:179], v[24:25], v[164:165] op_sel_hi:[1,0,1]
	ds_read_b128 v[24:27], v28 offset:39936
	ds_read_b128 v[164:167], v28 offset:40192
	ds_read_b128 v[168:171], v28 offset:40448
	ds_read_b128 v[172:175], v28 offset:40960
	ds_read_b128 v[176:179], v28 offset:41216
	ds_read_b32 v202, v29 offset:40704
	s_waitcnt lgkmcnt(6)
	v_pk_mul_f32 v[190:191], v[190:191], v[198:199]
	v_pk_mul_f32 v[34:35], v[34:35], v[198:199]
	v_pk_fma_f32 v[188:189], v[188:189], v[196:197], v[190:191]
	v_pk_fma_f32 v[32:33], v[32:33], v[196:197], v[34:35]
	v_add_f32_e32 v206, v188, v189
	v_add_f32_e32 v32, v32, v33
	v_pk_mul_f32 v[34:35], v[180:181], v[196:197]
	v_add_f32_dpp v33, v206, v206 quad_perm:[1,0,3,2] row_mask:0xf bank_mask:0xf bound_ctrl:1
	v_add_f32_dpp v32, v32, v32 quad_perm:[1,0,3,2] row_mask:0xf bank_mask:0xf bound_ctrl:1
	v_pk_mul_f32 v[180:181], v[182:183], v[198:199]
	v_add_f32_dpp v33, v33, v33 quad_perm:[2,3,0,1] row_mask:0xf bank_mask:0xf bound_ctrl:1
	v_add_f32_dpp v32, v32, v32 quad_perm:[2,3,0,1] row_mask:0xf bank_mask:0xf bound_ctrl:1
	v_pk_fma_f32 v[180:181], v[186:187], v[200:201], v[180:181] op_sel_hi:[1,0,1]
	v_add_f32_dpp v33, v33, v33 row_ror:4 row_mask:0xf bank_mask:0xf bound_ctrl:1
	v_add_f32_dpp v182, v32, v32 row_ror:4 row_mask:0xf bank_mask:0xf bound_ctrl:1
	v_pk_fma_f32 v[34:35], v[184:185], v[200:201], v[34:35] op_sel_hi:[1,0,1]
	v_add_f32_dpp v32, v33, v33 row_ror:8 row_mask:0xf bank_mask:0xf bound_ctrl:1
	v_add_f32_dpp v33, v182, v182 row_ror:8 row_mask:0xf bank_mask:0xf bound_ctrl:1
	v_pk_fma_f32 v[196:197], v[192:193], v[32:33], v[34:35] op_sel_hi:[1,0,1]
	v_cndmask_b32_e64 v31, v31, v33, s[22:23]
	v_pk_fma_f32 v[198:199], v[194:195], v[32:33], v[180:181] op_sel_hi:[1,0,1]
	ds_read_b128 v[32:35], v28 offset:41472
	ds_read_b128 v[180:183], v28 offset:41728
	ds_read_b128 v[184:187], v28 offset:41984
	ds_read_b128 v[188:191], v28 offset:42496
	ds_read_b128 v[192:195], v28 offset:42752
	ds_read_b32 v200, v29 offset:42240
	s_waitcnt lgkmcnt(6)
	v_pk_mul_f32 v[174:175], v[174:175], v[198:199]
	v_pk_mul_f32 v[162:163], v[162:163], v[198:199]
	v_pk_fma_f32 v[172:173], v[172:173], v[196:197], v[174:175]
	v_pk_fma_f32 v[160:161], v[160:161], v[196:197], v[162:163]
	v_add_f32_e32 v206, v172, v173
	v_add_f32_e32 v160, v160, v161
	v_pk_mul_f32 v[162:163], v[164:165], v[196:197]
	v_add_f32_dpp v161, v206, v206 quad_perm:[1,0,3,2] row_mask:0xf bank_mask:0xf bound_ctrl:1
	v_add_f32_dpp v160, v160, v160 quad_perm:[1,0,3,2] row_mask:0xf bank_mask:0xf bound_ctrl:1
	v_pk_mul_f32 v[164:165], v[166:167], v[198:199]
	v_add_f32_dpp v161, v161, v161 quad_perm:[2,3,0,1] row_mask:0xf bank_mask:0xf bound_ctrl:1
	v_add_f32_dpp v160, v160, v160 quad_perm:[2,3,0,1] row_mask:0xf bank_mask:0xf bound_ctrl:1
	v_pk_fma_f32 v[164:165], v[170:171], v[202:203], v[164:165] op_sel_hi:[1,0,1]
	v_add_f32_dpp v161, v161, v161 row_ror:4 row_mask:0xf bank_mask:0xf bound_ctrl:1
	v_add_f32_dpp v166, v160, v160 row_ror:4 row_mask:0xf bank_mask:0xf bound_ctrl:1
	v_pk_fma_f32 v[162:163], v[168:169], v[202:203], v[162:163] op_sel_hi:[1,0,1]
	v_add_f32_dpp v160, v161, v161 row_ror:8 row_mask:0xf bank_mask:0xf bound_ctrl:1
	v_add_f32_dpp v161, v166, v166 row_ror:8 row_mask:0xf bank_mask:0xf bound_ctrl:1
	v_pk_fma_f32 v[196:197], v[176:177], v[160:161], v[162:163] op_sel_hi:[1,0,1]
	v_cndmask_b32_e64 v31, v31, v161, s[24:25]
	v_pk_fma_f32 v[198:199], v[178:179], v[160:161], v[164:165] op_sel_hi:[1,0,1]
	ds_read_b128 v[160:163], v28 offset:43008
	ds_read_b128 v[164:167], v28 offset:43264
	ds_read_b128 v[168:171], v28 offset:43520
	ds_read_b128 v[172:175], v28 offset:44032
	ds_read_b128 v[176:179], v28 offset:44288
	ds_read_b32 v202, v29 offset:43776
	s_waitcnt lgkmcnt(6)
; #define LAS __attribute__((address_space(3)))
; __device__ __forceinline__ void rwkv_scan_prompt(const Params& p, LAS unsigned char* lds, int bh, int rq) {
;     ...
;             for (int tk = 0; tk < TC; ++tk) {
;                 f32x4 nr4 = r4, nd4 = d4, nk4 = k4, na4 = a4, nb4 = b4; float nvv = vv;
;                 if (tk < TC - 1) {
;                     const LAS float* o = ob + (tk + 1) * 6 * 64;
;                     nr4 = *(const LAS f32x4*)(o + cg_ * 4); nd4 = *(const LAS f32x4*)(o + 64 + cg_ * 4); nk4 = *(const LAS f32x4*)(o + 128 + cg_ * 4);
;                     na4 = *(const LAS f32x4*)(o + 256 + cg_ * 4); nb4 = *(const LAS f32x4*)(o + 320 + cg_ * 4);
;                     nvv = o[192 + rq * 16 + rloc];
;                 }
;                 __builtin_amdgcn_sched_barrier(0);
;                 typedef float f32x2_ __attribute__((ext_vector_type(2)));
;                 f32x2_ ta = (f32x2_){S[0], S[1]} * (f32x2_){a4[0], a4[1]}; ta = (f32x2_){S[2], S[3]} * (f32x2_){a4[2], a4[3]} + ta;
;                 f32x2_ ty = (f32x2_){S[0], S[1]} * (f32x2_){rp[0], rp[1]}; ty = (f32x2_){S[2], S[3]} * (f32x2_){rp[2], rp[3]} + ty;
;                 const f32x4 T = S * d4 + vv * k4;
;                 float sa = ta[0] + ta[1];
;                 float yp = ty[0] + ty[1];
;                 sa = dpp_add<0xB1>(sa); yp = dpp_add<0xB1>(yp);
;                 sa = dpp_add<0x4E>(sa); yp = dpp_add<0x4E>(yp);
;                 sa = dpp_add<0x124>(sa); yp = dpp_add<0x124>(yp);
;                 sa = dpp_add<0x128>(sa); yp = dpp_add<0x128>(yp);
;                 if (tk > 0) yk[(tk - 1) >> 4] = (cg_ == ((tk - 1) & 15)) ? yp : yk[(tk - 1) >> 4];
;                 S = sa * b4 + T;
;                 rp = r4;
;                 r4 = nr4; d4 = nd4; k4 = nk4; a4 = na4; b4 = nb4; vv = nvv;
;             }
	v_pk_mul_f32 v[190:191], v[190:191], v[198:199]
	v_pk_mul_f32 v[26:27], v[26:27], v[198:199]
	v_pk_fma_f32 v[188:189], v[188:189], v[196:197], v[190:191]
	v_pk_fma_f32 v[24:25], v[24:25], v[196:197], v[26:27]
	v_add_f32_e32 v206, v188, v189
	v_add_f32_e32 v24, v24, v25
	v_pk_mul_f32 v[26:27], v[180:181], v[196:197]
	v_add_f32_dpp v25, v206, v206 quad_perm:[1,0,3,2] row_mask:0xf bank_mask:0xf bound_ctrl:1
	v_add_f32_dpp v24, v24, v24 quad_perm:[1,0,3,2] row_mask:0xf bank_mask:0xf bound_ctrl:1
	v_pk_mul_f32 v[180:181], v[182:183], v[198:199]
	v_add_f32_dpp v25, v25, v25 quad_perm:[2,3,0,1] row_mask:0xf bank_mask:0xf bound_ctrl:1
	v_add_f32_dpp v24, v24, v24 quad_perm:[2,3,0,1] row_mask:0xf bank_mask:0xf bound_ctrl:1
	v_pk_fma_f32 v[180:181], v[186:187], v[200:201], v[180:181] op_sel_hi:[1,0,1]
	v_add_f32_dpp v25, v25, v25 row_ror:4 row_mask:0xf bank_mask:0xf bound_ctrl:1
	v_add_f32_dpp v182, v24, v24 row_ror:4 row_mask:0xf bank_mask:0xf bound_ctrl:1
	v_pk_fma_f32 v[26:27], v[184:185], v[200:201], v[26:27] op_sel_hi:[1,0,1]
	v_add_f32_dpp v24, v25, v25 row_ror:8 row_mask:0xf bank_mask:0xf bound_ctrl:1
	v_add_f32_dpp v25, v182, v182 row_ror:8 row_mask:0xf bank_mask:0xf bound_ctrl:1
	v_pk_fma_f32 v[196:197], v[192:193], v[24:25], v[26:27] op_sel_hi:[1,0,1]
	v_cndmask_b32_e64 v31, v31, v25, s[26:27]
	v_pk_fma_f32 v[198:199], v[194:195], v[24:25], v[180:181] op_sel_hi:[1,0,1]
	ds_read_b128 v[24:27], v28 offset:44544
	ds_read_b128 v[180:183], v28 offset:44800
	ds_read_b128 v[184:187], v28 offset:45056
	ds_read_b128 v[188:191], v28 offset:45568
	ds_read_b128 v[192:195], v28 offset:45824
	ds_read_b32 v200, v29 offset:45312
	s_waitcnt lgkmcnt(6)
	v_pk_mul_f32 v[174:175], v[174:175], v[198:199]
	v_pk_mul_f32 v[34:35], v[34:35], v[198:199]
	v_pk_fma_f32 v[172:173], v[172:173], v[196:197], v[174:175]
	v_pk_fma_f32 v[32:33], v[32:33], v[196:197], v[34:35]
	v_add_f32_e32 v206, v172, v173
	v_add_f32_e32 v32, v32, v33
	v_pk_mul_f32 v[34:35], v[164:165], v[196:197]
	v_add_f32_dpp v33, v206, v206 quad_perm:[1,0,3,2] row_mask:0xf bank_mask:0xf bound_ctrl:1
	v_add_f32_dpp v32, v32, v32 quad_perm:[1,0,3,2] row_mask:0xf bank_mask:0xf bound_ctrl:1
	v_pk_mul_f32 v[164:165], v[166:167], v[198:199]
	v_add_f32_dpp v33, v33, v33 quad_perm:[2,3,0,1] row_mask:0xf bank_mask:0xf bound_ctrl:1
	v_add_f32_dpp v32, v32, v32 quad_perm:[2,3,0,1] row_mask:0xf bank_mask:0xf bound_ctrl:1
	v_pk_fma_f32 v[164:165], v[170:171], v[202:203], v[164:165] op_sel_hi:[1,0,1]
	v_add_f32_dpp v33, v33, v33 row_ror:4 row_mask:0xf bank_mask:0xf bound_ctrl:1
	v_add_f32_dpp v166, v32, v32 row_ror:4 row_mask:0xf bank_mask:0xf bound_ctrl:1
	v_pk_fma_f32 v[34:35], v[168:169], v[202:203], v[34:35] op_sel_hi:[1,0,1]
	v_add_f32_dpp v32, v33, v33 row_ror:8 row_mask:0xf bank_mask:0xf bound_ctrl:1
	v_add_f32_dpp v33, v166, v166 row_ror:8 row_mask:0xf bank_mask:0xf bound_ctrl:1
	v_pk_fma_f32 v[196:197], v[176:177], v[32:33], v[34:35] op_sel_hi:[1,0,1]
	v_cndmask_b32_e64 v31, v31, v33, s[28:29]
	v_pk_fma_f32 v[198:199], v[178:179], v[32:33], v[164:165] op_sel_hi:[1,0,1]
	ds_read_b128 v[32:35], v28 offset:46080
	ds_read_b128 v[164:167], v28 offset:46336
	ds_read_b128 v[168:171], v28 offset:46592
	ds_read_b128 v[172:175], v28 offset:47104
	ds_read_b128 v[176:179], v28 offset:47360
	ds_read_b32 v202, v29 offset:46848
	s_waitcnt lgkmcnt(6)
	v_pk_mul_f32 v[190:191], v[190:191], v[198:199]
	v_pk_mul_f32 v[162:163], v[162:163], v[198:199]
	v_pk_fma_f32 v[188:189], v[188:189], v[196:197], v[190:191]
	v_pk_fma_f32 v[160:161], v[160:161], v[196:197], v[162:163]
	v_add_f32_e32 v206, v188, v189
	v_add_f32_e32 v160, v160, v161
	v_pk_mul_f32 v[162:163], v[180:181], v[196:197]
	v_add_f32_dpp v161, v206, v206 quad_perm:[1,0,3,2] row_mask:0xf bank_mask:0xf bound_ctrl:1
	v_add_f32_dpp v160, v160, v160 quad_perm:[1,0,3,2] row_mask:0xf bank_mask:0xf bound_ctrl:1
	v_pk_mul_f32 v[180:181], v[182:183], v[198:199]
	v_add_f32_dpp v161, v161, v161 quad_perm:[2,3,0,1] row_mask:0xf bank_mask:0xf bound_ctrl:1
	v_add_f32_dpp v160, v160, v160 quad_perm:[2,3,0,1] row_mask:0xf bank_mask:0xf bound_ctrl:1
	v_pk_fma_f32 v[180:181], v[186:187], v[200:201], v[180:181] op_sel_hi:[1,0,1]
	v_add_f32_dpp v161, v161, v161 row_ror:4 row_mask:0xf bank_mask:0xf bound_ctrl:1
	v_add_f32_dpp v182, v160, v160 row_ror:4 row_mask:0xf bank_mask:0xf bound_ctrl:1
	v_pk_fma_f32 v[162:163], v[184:185], v[200:201], v[162:163] op_sel_hi:[1,0,1]
	v_add_f32_dpp v160, v161, v161 row_ror:8 row_mask:0xf bank_mask:0xf bound_ctrl:1
	v_add_f32_dpp v161, v182, v182 row_ror:8 row_mask:0xf bank_mask:0xf bound_ctrl:1
	v_pk_fma_f32 v[196:197], v[192:193], v[160:161], v[162:163] op_sel_hi:[1,0,1]
	v_cndmask_b32_e64 v31, v31, v161, s[30:31]
	v_pk_fma_f32 v[198:199], v[194:195], v[160:161], v[180:181] op_sel_hi:[1,0,1]
	ds_read_b128 v[160:163], v28 offset:47616
	ds_read_b128 v[180:183], v28 offset:47872
	ds_read_b128 v[184:187], v28 offset:48128
	ds_read_b128 v[188:191], v28 offset:48640
	ds_read_b128 v[192:195], v28 offset:48896
	ds_read_b32 v28, v29 offset:48384
	s_waitcnt lgkmcnt(6)
; #define LAS __attribute__((address_space(3)))
; __device__ __forceinline__ void rwkv_scan_prompt(const Params& p, LAS unsigned char* lds, int bh, int rq) {
;     ...
;             for (int tk = 0; tk < TC; ++tk) {
;                 f32x4 nr4 = r4, nd4 = d4, nk4 = k4, na4 = a4, nb4 = b4; float nvv = vv;
;                 if (tk < TC - 1) {
;                     const LAS float* o = ob + (tk + 1) * 6 * 64;
;                     nr4 = *(const LAS f32x4*)(o + cg_ * 4); nd4 = *(const LAS f32x4*)(o + 64 + cg_ * 4); nk4 = *(const LAS f32x4*)(o + 128 + cg_ * 4);
;                     na4 = *(const LAS f32x4*)(o + 256 + cg_ * 4); nb4 = *(const LAS f32x4*)(o + 320 + cg_ * 4);
;                     nvv = o[192 + rq * 16 + rloc];
;                 }
;                 __builtin_amdgcn_sched_barrier(0);
;                 typedef float f32x2_ __attribute__((ext_vector_type(2)));
;                 f32x2_ ta = (f32x2_){S[0], S[1]} * (f32x2_){a4[0], a4[1]}; ta = (f32x2_){S[2], S[3]} * (f32x2_){a4[2], a4[3]} + ta;
;                 f32x2_ ty = (f32x2_){S[0], S[1]} * (f32x2_){rp[0], rp[1]}; ty = (f32x2_){S[2], S[3]} * (f32x2_){rp[2], rp[3]} + ty;
;                 const f32x4 T = S * d4 + vv * k4;
;                 float sa = ta[0] + ta[1];
;                 float yp = ty[0] + ty[1];
;                 sa = dpp_add<0xB1>(sa); yp = dpp_add<0xB1>(yp);
;                 sa = dpp_add<0x4E>(sa); yp = dpp_add<0x4E>(yp);
;                 sa = dpp_add<0x124>(sa); yp = dpp_add<0x124>(yp);
;                 sa = dpp_add<0x128>(sa); yp = dpp_add<0x128>(yp);
;                 if (tk > 0) yk[(tk - 1) >> 4] = (cg_ == ((tk - 1) & 15)) ? yp : yk[(tk - 1) >> 4];
;                 S = sa * b4 + T;
;                 rp = r4;
;                 r4 = nr4; d4 = nd4; k4 = nk4; a4 = na4; b4 = nb4; vv = nvv;
;             }
;             {
;                 float yp = S[0] * rp[0] + S[1] * rp[1] + S[2] * rp[2] + S[3] * rp[3];
;                 yp = row_sum16(yp);
;                 yk[(TC - 1) >> 4] = (cg_ == ((TC - 1) & 15)) ? yp : yk[(TC - 1) >> 4];
;             }
; #pragma unroll
;             for (int j = 0; j < TC / 16; ++j) yk[j] += RKB[buf * TC + j * 16 + cg_] * ob[(j * 16 + cg_) * 6 * 64 + 192 + rq * 16 + rloc];
; #pragma unroll
;             for (int j = 0; j < TC / 16; ++j) YRAW[(size_t)(rowbase + c * TC + j * 16 + cg_) * 512 + h * 64 + rq * 16 + rloc] = yk[j];
	v_pk_mul_f32 v[174:175], v[174:175], v[198:199]
	v_pk_mul_f32 v[26:27], v[26:27], v[198:199]
	v_pk_fma_f32 v[172:173], v[172:173], v[196:197], v[174:175]
	v_pk_fma_f32 v[24:25], v[24:25], v[196:197], v[26:27]
	v_add_f32_e32 v206, v172, v173
	v_add_f32_e32 v24, v24, v25
	v_pk_mul_f32 v[26:27], v[164:165], v[196:197]
	v_add_f32_dpp v25, v206, v206 quad_perm:[1,0,3,2] row_mask:0xf bank_mask:0xf bound_ctrl:1
	v_add_f32_dpp v24, v24, v24 quad_perm:[1,0,3,2] row_mask:0xf bank_mask:0xf bound_ctrl:1
	v_pk_mul_f32 v[164:165], v[166:167], v[198:199]
	v_add_f32_dpp v25, v25, v25 quad_perm:[2,3,0,1] row_mask:0xf bank_mask:0xf bound_ctrl:1
	v_add_f32_dpp v24, v24, v24 quad_perm:[2,3,0,1] row_mask:0xf bank_mask:0xf bound_ctrl:1
	v_pk_fma_f32 v[164:165], v[170:171], v[202:203], v[164:165] op_sel_hi:[1,0,1]
	v_add_f32_dpp v25, v25, v25 row_ror:4 row_mask:0xf bank_mask:0xf bound_ctrl:1
	v_add_f32_dpp v29, v24, v24 row_ror:4 row_mask:0xf bank_mask:0xf bound_ctrl:1
	v_pk_fma_f32 v[26:27], v[168:169], v[202:203], v[26:27] op_sel_hi:[1,0,1]
	v_add_f32_dpp v24, v25, v25 row_ror:8 row_mask:0xf bank_mask:0xf bound_ctrl:1
	v_add_f32_dpp v25, v29, v29 row_ror:8 row_mask:0xf bank_mask:0xf bound_ctrl:1
	v_pk_fma_f32 v[26:27], v[176:177], v[24:25], v[26:27] op_sel_hi:[1,0,1]
	v_cndmask_b32_e64 v29, v31, v25, s[34:35]
	v_pk_fma_f32 v[24:25], v[178:179], v[24:25], v[164:165] op_sel_hi:[1,0,1]
	s_waitcnt lgkmcnt(2)
	v_pk_mul_f32 v[164:165], v[190:191], v[24:25]
	v_pk_mul_f32 v[34:35], v[34:35], v[24:25]
	v_pk_fma_f32 v[164:165], v[188:189], v[26:27], v[164:165]
	v_pk_fma_f32 v[32:33], v[32:33], v[26:27], v[34:35]
	v_pk_mul_f32 v[26:27], v[180:181], v[26:27]
	v_pk_mul_f32 v[24:25], v[182:183], v[24:25]
	s_waitcnt lgkmcnt(0)
	v_pk_fma_f32 v[34:35], v[184:185], v[28:29], v[26:27] op_sel_hi:[1,0,1]
	v_add_f32_e32 v26, v164, v165
	v_add_f32_e32 v27, v32, v33
	v_pk_fma_f32 v[24:25], v[186:187], v[28:29], v[24:25] op_sel_hi:[1,0,1]
	v_add_f32_dpp v26, v26, v26 quad_perm:[1,0,3,2] row_mask:0xf bank_mask:0xf bound_ctrl:1
	v_add_f32_dpp v27, v27, v27 quad_perm:[1,0,3,2] row_mask:0xf bank_mask:0xf bound_ctrl:1
	s_lshl_b32 s79, s94, 2
	v_add_f32_dpp v26, v26, v26 quad_perm:[2,3,0,1] row_mask:0xf bank_mask:0xf bound_ctrl:1
	v_add_f32_dpp v27, v27, v27 quad_perm:[2,3,0,1] row_mask:0xf bank_mask:0xf bound_ctrl:1
	s_add_i32 s79, s79, s78
	v_add_f32_dpp v26, v26, v26 row_ror:4 row_mask:0xf bank_mask:0xf bound_ctrl:1
	v_add_f32_dpp v27, v27, v27 row_ror:4 row_mask:0xf bank_mask:0xf bound_ctrl:1
	v_add3_u32 v32, s79, v135, v84
	v_add_f32_dpp v28, v26, v26 row_ror:8 row_mask:0xf bank_mask:0xf bound_ctrl:1
	v_add_f32_dpp v26, v27, v27 row_ror:8 row_mask:0xf bank_mask:0xf bound_ctrl:1
	v_cndmask_b32_e64 v31, v29, v26, s[36:37]
	v_pk_fma_f32 v[26:27], v[194:195], v[28:29], v[24:25] op_sel_hi:[1,0,1]
	v_pk_fma_f32 v[24:25], v[192:193], v[28:29], v[34:35] op_sel_hi:[1,0,1]
	ds_read2st64_b32 v[32:33], v32 offset0:3 offset1:99
	v_mul_f32_e32 v28, v161, v25
	v_fmac_f32_e32 v28, v160, v24
	v_fmac_f32_e32 v28, v162, v26
	v_fmac_f32_e32 v28, v163, v27
	s_nop 1
	v_add_f32_dpp v34, v28, v28 quad_perm:[1,0,3,2] row_mask:0xf bank_mask:0xf bound_ctrl:1
	v_lshl_add_u32 v28, s95, 7, v126
	ds_read2_b32 v[28:29], v28 offset1:16
	v_add_f32_dpp v34, v34, v34 quad_perm:[2,3,0,1] row_mask:0xf bank_mask:0xf bound_ctrl:1
	s_waitcnt lgkmcnt(0)
	v_fmac_f32_e32 v30, v28, v32
	v_add_f32_dpp v34, v34, v34 row_ror:4 row_mask:0xf bank_mask:0xf bound_ctrl:1
	v_add_u32_e32 v28, s0, v159
	s_nop 0
	v_add_f32_dpp v34, v34, v34 row_ror:8 row_mask:0xf bank_mask:0xf bound_ctrl:1
	v_cndmask_b32_e64 v31, v31, v34, s[4:5]
	v_fmac_f32_e32 v31, v29, v33
	v_ashrrev_i32_e32 v29, 31, v28
	v_lshlrev_b64 v[32:33], 11, v[28:29]
	v_add_u32_e32 v28, 16, v28
	v_ashrrev_i32_e32 v29, 31, v28
	v_lshlrev_b64 v[28:29], 11, v[28:29]
	v_lshl_add_u64 v[32:33], v[88:89], 0, v[32:33]
	v_lshl_add_u64 v[28:29], v[88:89], 0, v[28:29]
	global_store_dword v[32:33], v30, off sc0 sc1
	global_store_dword v[28:29], v31, off sc0 sc1
